# epilogue-ss-loads-hoisted-counted-vmcnt-kinds123+conv-loads-batched+moba-prefetch
# speedup vs baseline: 1.0150x; 1.0150x over previous
.LBB0_148:
	s_or_b64 exec, exec, s[36:37]
	v_lshlrev_b64 v[42:43], 11, v[32:33]
	v_or_b32_e32 v42, v42, v96
	v_lshl_add_u64 v[38:39], s[24:25], 0, v[42:43]
	v_lshl_add_u64 v[40:41], s[26:27], 0, v[42:43]
	v_lshl_add_u64 v[44:45], v[38:39], 0, s[10:11]
	v_lshl_add_u64 v[50:51], v[40:41], 0, s[10:11]
	v_lshl_add_u64 v[46:47], v[44:45], 0, s[10:11]
	v_lshl_add_u64 v[52:53], v[50:51], 0, s[10:11]
	v_lshl_add_u64 v[48:49], v[46:47], 0, s[10:11]
	v_lshl_add_u64 v[54:55], v[52:53], 0, s[10:11]
	global_load_dwordx4 v[56:59], v[38:39], off
	global_load_dwordx4 v[88:91], v[40:41], off
	global_load_dwordx4 v[60:63], v[38:39], off offset:2048
	global_load_dwordx4 v[92:95], v[40:41], off offset:2048
	global_load_dwordx4 v[64:67], v[44:45], off
	global_load_dwordx4 v[98:101], v[50:51], off
	global_load_dwordx4 v[68:71], v[44:45], off offset:2048
	global_load_dwordx4 v[102:105], v[50:51], off offset:2048
	global_load_dwordx4 v[72:75], v[46:47], off
	global_load_dwordx4 v[106:109], v[52:53], off
	global_load_dwordx4 v[76:79], v[46:47], off offset:2048
	global_load_dwordx4 v[110:113], v[52:53], off offset:2048
	global_load_dwordx4 v[80:83], v[48:49], off
	global_load_dwordx4 v[114:117], v[54:55], off
	global_load_dwordx4 v[84:87], v[48:49], off offset:2048
	global_load_dwordx4 v[118:121], v[54:55], off offset:2048
	v_add_u32_e32 v34, s72, v34
	v_cmp_lt_i32_e32 vcc, s68, v34
	s_or_b64 s[30:31], vcc, s[30:31]
	v_add_u32_e32 v35, s8, v35
	s_waitcnt vmcnt(14)
	v_lshlrev_b32_e32 v122, 16, v28
	v_and_b32_e32 v123, 0xffff0000, v28
	v_lshlrev_b32_e32 v124, 16, v29
	v_and_b32_e32 v125, 0xffff0000, v29
	v_lshlrev_b32_e32 v126, 16, v30
	v_and_b32_e32 v127, 0xffff0000, v30
	v_lshlrev_b32_e32 v128, 16, v31
	v_and_b32_e32 v129, 0xffff0000, v31
	v_lshlrev_b32_e32 v130, 16, v24
	v_and_b32_e32 v131, 0xffff0000, v24
	v_lshlrev_b32_e32 v132, 16, v25
	v_and_b32_e32 v133, 0xffff0000, v25
	v_lshlrev_b32_e32 v134, 16, v26
	v_and_b32_e32 v135, 0xffff0000, v26
	v_lshlrev_b32_e32 v136, 16, v27
	v_and_b32_e32 v137, 0xffff0000, v27
	v_lshlrev_b32_e32 v138, 16, v56
	v_and_b32_e32 v139, 0xffff0000, v56
	v_lshlrev_b32_e32 v140, 16, v57
	v_and_b32_e32 v141, 0xffff0000, v57
	v_lshlrev_b32_e32 v142, 16, v58
	v_and_b32_e32 v143, 0xffff0000, v58
	v_lshlrev_b32_e32 v144, 16, v59
	v_and_b32_e32 v145, 0xffff0000, v59
	v_lshlrev_b32_e32 v146, 16, v88
	v_and_b32_e32 v147, 0xffff0000, v88
	v_lshlrev_b32_e32 v148, 16, v89
	v_and_b32_e32 v149, 0xffff0000, v89
	v_lshlrev_b32_e32 v150, 16, v90
	v_and_b32_e32 v151, 0xffff0000, v90
	v_lshlrev_b32_e32 v152, 16, v91
	v_and_b32_e32 v153, 0xffff0000, v91
	v_pk_mul_f32 v[154:155], v[12:13], v[122:123]
	v_pk_mul_f32 v[156:157], v[14:15], v[124:125]
	v_pk_mul_f32 v[158:159], v[0:1], v[126:127]
	v_pk_mul_f32 v[160:161], v[2:3], v[128:129]
	v_pk_fma_f32 v[154:155], v[20:21], v[130:131], v[154:155]
	v_pk_fma_f32 v[156:157], v[22:23], v[132:133], v[156:157]
	v_pk_fma_f32 v[158:159], v[16:17], v[134:135], v[158:159]
	v_pk_fma_f32 v[160:161], v[18:19], v[136:137], v[160:161]
	v_pk_fma_f32 v[154:155], v[8:9], v[138:139], v[154:155]
	v_pk_fma_f32 v[156:157], v[10:11], v[140:141], v[156:157]
	v_pk_fma_f32 v[158:159], v[4:5], v[142:143], v[158:159]
	v_pk_fma_f32 v[160:161], v[6:7], v[144:145], v[160:161]
	v_pk_mul_f32 v[154:155], v[154:155], v[146:147]
	v_pk_mul_f32 v[156:157], v[156:157], v[148:149]
	v_pk_mul_f32 v[158:159], v[158:159], v[150:151]
	v_pk_mul_f32 v[160:161], v[160:161], v[152:153]
	v_cvt_pk_bf16_f32 v162, v154, v155
	v_cvt_pk_bf16_f32 v163, v156, v157
	v_cvt_pk_bf16_f32 v164, v158, v159
	v_cvt_pk_bf16_f32 v165, v160, v161
	global_store_dwordx4 v[40:41], v[162:165], off nt
	s_waitcnt vmcnt(13)
	v_lshlrev_b32_e32 v122, 16, v60
	v_and_b32_e32 v123, 0xffff0000, v60
	v_lshlrev_b32_e32 v124, 16, v61
	v_and_b32_e32 v125, 0xffff0000, v61
	v_lshlrev_b32_e32 v126, 16, v62
	v_and_b32_e32 v127, 0xffff0000, v62
	v_lshlrev_b32_e32 v128, 16, v63
	v_and_b32_e32 v129, 0xffff0000, v63
	v_lshlrev_b32_e32 v146, 16, v92
	v_and_b32_e32 v147, 0xffff0000, v92
	v_lshlrev_b32_e32 v148, 16, v93
	v_and_b32_e32 v149, 0xffff0000, v93
	v_lshlrev_b32_e32 v150, 16, v94
	v_and_b32_e32 v151, 0xffff0000, v94
	v_lshlrev_b32_e32 v152, 16, v95
	v_and_b32_e32 v153, 0xffff0000, v95
	v_pk_mul_f32 v[154:155], v[20:21], v[138:139]
	v_pk_mul_f32 v[156:157], v[22:23], v[140:141]
	v_pk_mul_f32 v[158:159], v[16:17], v[142:143]
	v_pk_mul_f32 v[160:161], v[18:19], v[144:145]
	v_pk_fma_f32 v[154:155], v[12:13], v[130:131], v[154:155]
	v_pk_fma_f32 v[156:157], v[14:15], v[132:133], v[156:157]
	v_pk_fma_f32 v[158:159], v[0:1], v[134:135], v[158:159]
	v_pk_fma_f32 v[160:161], v[2:3], v[136:137], v[160:161]
	v_pk_fma_f32 v[154:155], v[8:9], v[122:123], v[154:155]
	v_pk_fma_f32 v[156:157], v[10:11], v[124:125], v[156:157]
	v_pk_fma_f32 v[158:159], v[4:5], v[126:127], v[158:159]
	v_pk_fma_f32 v[160:161], v[6:7], v[128:129], v[160:161]
	v_pk_mul_f32 v[154:155], v[154:155], v[146:147]
	v_pk_mul_f32 v[156:157], v[156:157], v[148:149]
	v_pk_mul_f32 v[158:159], v[158:159], v[150:151]
	v_pk_mul_f32 v[160:161], v[160:161], v[152:153]
	v_cvt_pk_bf16_f32 v166, v154, v155
	v_cvt_pk_bf16_f32 v167, v156, v157
	v_cvt_pk_bf16_f32 v168, v158, v159
	v_cvt_pk_bf16_f32 v169, v160, v161
	global_store_dwordx4 v[40:41], v[166:169], off offset:2048 nt
	s_waitcnt vmcnt(12)
	v_lshlrev_b32_e32 v130, 16, v64
	v_and_b32_e32 v131, 0xffff0000, v64
	v_lshlrev_b32_e32 v132, 16, v65
	v_and_b32_e32 v133, 0xffff0000, v65
	v_lshlrev_b32_e32 v134, 16, v66
	v_and_b32_e32 v135, 0xffff0000, v66
	v_lshlrev_b32_e32 v136, 16, v67
	v_and_b32_e32 v137, 0xffff0000, v67
	v_lshlrev_b32_e32 v146, 16, v98
	v_and_b32_e32 v147, 0xffff0000, v98
	v_lshlrev_b32_e32 v148, 16, v99
	v_and_b32_e32 v149, 0xffff0000, v99
	v_lshlrev_b32_e32 v150, 16, v100
	v_and_b32_e32 v151, 0xffff0000, v100
	v_lshlrev_b32_e32 v152, 16, v101
	v_and_b32_e32 v153, 0xffff0000, v101
	v_pk_mul_f32 v[154:155], v[20:21], v[122:123]
	v_pk_mul_f32 v[156:157], v[22:23], v[124:125]
	v_pk_mul_f32 v[158:159], v[16:17], v[126:127]
	v_pk_mul_f32 v[160:161], v[18:19], v[128:129]
	v_pk_fma_f32 v[154:155], v[12:13], v[138:139], v[154:155]
	v_pk_fma_f32 v[156:157], v[14:15], v[140:141], v[156:157]
	v_pk_fma_f32 v[158:159], v[0:1], v[142:143], v[158:159]
	v_pk_fma_f32 v[160:161], v[2:3], v[144:145], v[160:161]
	v_pk_fma_f32 v[154:155], v[8:9], v[130:131], v[154:155]
	v_pk_fma_f32 v[156:157], v[10:11], v[132:133], v[156:157]
	v_pk_fma_f32 v[158:159], v[4:5], v[134:135], v[158:159]
	v_pk_fma_f32 v[160:161], v[6:7], v[136:137], v[160:161]
	v_pk_mul_f32 v[154:155], v[154:155], v[146:147]
	v_pk_mul_f32 v[156:157], v[156:157], v[148:149]
	v_pk_mul_f32 v[158:159], v[158:159], v[150:151]
	v_pk_mul_f32 v[160:161], v[160:161], v[152:153]
	v_cvt_pk_bf16_f32 v162, v154, v155
	v_cvt_pk_bf16_f32 v163, v156, v157
	v_cvt_pk_bf16_f32 v164, v158, v159
	v_cvt_pk_bf16_f32 v165, v160, v161
	global_store_dwordx4 v[50:51], v[162:165], off nt
	s_waitcnt vmcnt(11)
	v_lshlrev_b32_e32 v138, 16, v68
	v_and_b32_e32 v139, 0xffff0000, v68
	v_lshlrev_b32_e32 v140, 16, v69
	v_and_b32_e32 v141, 0xffff0000, v69
	v_lshlrev_b32_e32 v142, 16, v70
	v_and_b32_e32 v143, 0xffff0000, v70
	v_lshlrev_b32_e32 v144, 16, v71
	v_and_b32_e32 v145, 0xffff0000, v71
	v_lshlrev_b32_e32 v146, 16, v102
	v_and_b32_e32 v147, 0xffff0000, v102
	v_lshlrev_b32_e32 v148, 16, v103
	v_and_b32_e32 v149, 0xffff0000, v103
	v_lshlrev_b32_e32 v150, 16, v104
	v_and_b32_e32 v151, 0xffff0000, v104
	v_lshlrev_b32_e32 v152, 16, v105
	v_and_b32_e32 v153, 0xffff0000, v105
	v_pk_mul_f32 v[154:155], v[20:21], v[130:131]
	v_pk_mul_f32 v[156:157], v[22:23], v[132:133]
	v_pk_mul_f32 v[158:159], v[16:17], v[134:135]
	v_pk_mul_f32 v[160:161], v[18:19], v[136:137]
	v_pk_fma_f32 v[154:155], v[12:13], v[122:123], v[154:155]
	v_pk_fma_f32 v[156:157], v[14:15], v[124:125], v[156:157]
	v_pk_fma_f32 v[158:159], v[0:1], v[126:127], v[158:159]
	v_pk_fma_f32 v[160:161], v[2:3], v[128:129], v[160:161]
	v_pk_fma_f32 v[154:155], v[8:9], v[138:139], v[154:155]
	v_pk_fma_f32 v[156:157], v[10:11], v[140:141], v[156:157]
	v_pk_fma_f32 v[158:159], v[4:5], v[142:143], v[158:159]
	v_pk_fma_f32 v[160:161], v[6:7], v[144:145], v[160:161]
	v_pk_mul_f32 v[154:155], v[154:155], v[146:147]
	v_pk_mul_f32 v[156:157], v[156:157], v[148:149]
	v_pk_mul_f32 v[158:159], v[158:159], v[150:151]
	v_pk_mul_f32 v[160:161], v[160:161], v[152:153]
	v_cvt_pk_bf16_f32 v166, v154, v155
	v_cvt_pk_bf16_f32 v167, v156, v157
	v_cvt_pk_bf16_f32 v168, v158, v159
	v_cvt_pk_bf16_f32 v169, v160, v161
	global_store_dwordx4 v[50:51], v[166:169], off offset:2048 nt
	s_waitcnt vmcnt(10)
	v_lshlrev_b32_e32 v122, 16, v72
	v_and_b32_e32 v123, 0xffff0000, v72
	v_lshlrev_b32_e32 v124, 16, v73
	v_and_b32_e32 v125, 0xffff0000, v73
	v_lshlrev_b32_e32 v126, 16, v74
	v_and_b32_e32 v127, 0xffff0000, v74
	v_lshlrev_b32_e32 v128, 16, v75
	v_and_b32_e32 v129, 0xffff0000, v75
	v_lshlrev_b32_e32 v146, 16, v106
	v_and_b32_e32 v147, 0xffff0000, v106
	v_lshlrev_b32_e32 v148, 16, v107
	v_and_b32_e32 v149, 0xffff0000, v107
	v_lshlrev_b32_e32 v150, 16, v108
	v_and_b32_e32 v151, 0xffff0000, v108
	v_lshlrev_b32_e32 v152, 16, v109
	v_and_b32_e32 v153, 0xffff0000, v109
	v_pk_mul_f32 v[154:155], v[20:21], v[138:139]
	v_pk_mul_f32 v[156:157], v[22:23], v[140:141]
	v_pk_mul_f32 v[158:159], v[16:17], v[142:143]
	v_pk_mul_f32 v[160:161], v[18:19], v[144:145]
	v_pk_fma_f32 v[154:155], v[12:13], v[130:131], v[154:155]
	v_pk_fma_f32 v[156:157], v[14:15], v[132:133], v[156:157]
	v_pk_fma_f32 v[158:159], v[0:1], v[134:135], v[158:159]
	v_pk_fma_f32 v[160:161], v[2:3], v[136:137], v[160:161]
	v_pk_fma_f32 v[154:155], v[8:9], v[122:123], v[154:155]
	v_pk_fma_f32 v[156:157], v[10:11], v[124:125], v[156:157]
	v_pk_fma_f32 v[158:159], v[4:5], v[126:127], v[158:159]
	v_pk_fma_f32 v[160:161], v[6:7], v[128:129], v[160:161]
	v_pk_mul_f32 v[154:155], v[154:155], v[146:147]
	v_pk_mul_f32 v[156:157], v[156:157], v[148:149]
	v_pk_mul_f32 v[158:159], v[158:159], v[150:151]
	v_pk_mul_f32 v[160:161], v[160:161], v[152:153]
	v_cvt_pk_bf16_f32 v162, v154, v155
	v_cvt_pk_bf16_f32 v163, v156, v157
	v_cvt_pk_bf16_f32 v164, v158, v159
	v_cvt_pk_bf16_f32 v165, v160, v161
	global_store_dwordx4 v[52:53], v[162:165], off nt
	s_waitcnt vmcnt(9)
	v_lshlrev_b32_e32 v130, 16, v76
	v_and_b32_e32 v131, 0xffff0000, v76
	v_lshlrev_b32_e32 v132, 16, v77
	v_and_b32_e32 v133, 0xffff0000, v77
	v_lshlrev_b32_e32 v134, 16, v78
	v_and_b32_e32 v135, 0xffff0000, v78
	v_lshlrev_b32_e32 v136, 16, v79
	v_and_b32_e32 v137, 0xffff0000, v79
	v_lshlrev_b32_e32 v146, 16, v110
	v_and_b32_e32 v147, 0xffff0000, v110
	v_lshlrev_b32_e32 v148, 16, v111
	v_and_b32_e32 v149, 0xffff0000, v111
	v_lshlrev_b32_e32 v150, 16, v112
	v_and_b32_e32 v151, 0xffff0000, v112
	v_lshlrev_b32_e32 v152, 16, v113
	v_and_b32_e32 v153, 0xffff0000, v113
	v_pk_mul_f32 v[154:155], v[20:21], v[122:123]
	v_pk_mul_f32 v[156:157], v[22:23], v[124:125]
	v_pk_mul_f32 v[158:159], v[16:17], v[126:127]
	v_pk_mul_f32 v[160:161], v[18:19], v[128:129]
	v_pk_fma_f32 v[154:155], v[12:13], v[138:139], v[154:155]
	v_pk_fma_f32 v[156:157], v[14:15], v[140:141], v[156:157]
	v_pk_fma_f32 v[158:159], v[0:1], v[142:143], v[158:159]
	v_pk_fma_f32 v[160:161], v[2:3], v[144:145], v[160:161]
	v_pk_fma_f32 v[154:155], v[8:9], v[130:131], v[154:155]
	v_pk_fma_f32 v[156:157], v[10:11], v[132:133], v[156:157]
	v_pk_fma_f32 v[158:159], v[4:5], v[134:135], v[158:159]
	v_pk_fma_f32 v[160:161], v[6:7], v[136:137], v[160:161]
	v_pk_mul_f32 v[154:155], v[154:155], v[146:147]
	v_pk_mul_f32 v[156:157], v[156:157], v[148:149]
	v_pk_mul_f32 v[158:159], v[158:159], v[150:151]
	v_pk_mul_f32 v[160:161], v[160:161], v[152:153]
	v_cvt_pk_bf16_f32 v166, v154, v155
	v_cvt_pk_bf16_f32 v167, v156, v157
	v_cvt_pk_bf16_f32 v168, v158, v159
	v_cvt_pk_bf16_f32 v169, v160, v161
	global_store_dwordx4 v[52:53], v[166:169], off offset:2048 nt
	s_waitcnt vmcnt(8)
	v_lshlrev_b32_e32 v138, 16, v80
	v_and_b32_e32 v139, 0xffff0000, v80
	v_lshlrev_b32_e32 v140, 16, v81
	v_and_b32_e32 v141, 0xffff0000, v81
	v_lshlrev_b32_e32 v142, 16, v82
	v_and_b32_e32 v143, 0xffff0000, v82
	v_lshlrev_b32_e32 v144, 16, v83
	v_and_b32_e32 v145, 0xffff0000, v83
	v_lshlrev_b32_e32 v146, 16, v114
	v_and_b32_e32 v147, 0xffff0000, v114
	v_lshlrev_b32_e32 v148, 16, v115
	v_and_b32_e32 v149, 0xffff0000, v115
	v_lshlrev_b32_e32 v150, 16, v116
	v_and_b32_e32 v151, 0xffff0000, v116
	v_lshlrev_b32_e32 v152, 16, v117
	v_and_b32_e32 v153, 0xffff0000, v117
	v_pk_mul_f32 v[154:155], v[20:21], v[130:131]
	v_pk_mul_f32 v[156:157], v[22:23], v[132:133]
	v_pk_mul_f32 v[158:159], v[16:17], v[134:135]
	v_pk_mul_f32 v[160:161], v[18:19], v[136:137]
	v_pk_fma_f32 v[154:155], v[12:13], v[122:123], v[154:155]
	v_pk_fma_f32 v[156:157], v[14:15], v[124:125], v[156:157]
	v_pk_fma_f32 v[158:159], v[0:1], v[126:127], v[158:159]
	v_pk_fma_f32 v[160:161], v[2:3], v[128:129], v[160:161]
	v_pk_fma_f32 v[154:155], v[8:9], v[138:139], v[154:155]
	v_pk_fma_f32 v[156:157], v[10:11], v[140:141], v[156:157]
	v_pk_fma_f32 v[158:159], v[4:5], v[142:143], v[158:159]
	v_pk_fma_f32 v[160:161], v[6:7], v[144:145], v[160:161]
	v_pk_mul_f32 v[154:155], v[154:155], v[146:147]
	v_pk_mul_f32 v[156:157], v[156:157], v[148:149]
	v_pk_mul_f32 v[158:159], v[158:159], v[150:151]
	v_pk_mul_f32 v[160:161], v[160:161], v[152:153]
	v_cvt_pk_bf16_f32 v162, v154, v155
	v_cvt_pk_bf16_f32 v163, v156, v157
	v_cvt_pk_bf16_f32 v164, v158, v159
	v_cvt_pk_bf16_f32 v165, v160, v161
	global_store_dwordx4 v[54:55], v[162:165], off nt
	s_waitcnt vmcnt(7)
	v_lshlrev_b32_e32 v122, 16, v84
	v_and_b32_e32 v123, 0xffff0000, v84
	v_lshlrev_b32_e32 v124, 16, v85
	v_and_b32_e32 v125, 0xffff0000, v85
	v_lshlrev_b32_e32 v126, 16, v86
	v_and_b32_e32 v127, 0xffff0000, v86
	v_lshlrev_b32_e32 v128, 16, v87
	v_and_b32_e32 v129, 0xffff0000, v87
	v_lshlrev_b32_e32 v146, 16, v118
	v_and_b32_e32 v147, 0xffff0000, v118
	v_lshlrev_b32_e32 v148, 16, v119
	v_and_b32_e32 v149, 0xffff0000, v119
	v_lshlrev_b32_e32 v150, 16, v120
	v_and_b32_e32 v151, 0xffff0000, v120
	v_lshlrev_b32_e32 v152, 16, v121
	v_and_b32_e32 v153, 0xffff0000, v121
	v_pk_mul_f32 v[154:155], v[20:21], v[138:139]
	v_pk_mul_f32 v[156:157], v[22:23], v[140:141]
	v_pk_mul_f32 v[158:159], v[16:17], v[142:143]
	v_pk_mul_f32 v[160:161], v[18:19], v[144:145]
	v_pk_fma_f32 v[154:155], v[12:13], v[130:131], v[154:155]
	v_pk_fma_f32 v[156:157], v[14:15], v[132:133], v[156:157]
	v_pk_fma_f32 v[158:159], v[0:1], v[134:135], v[158:159]
	v_pk_fma_f32 v[160:161], v[2:3], v[136:137], v[160:161]
	v_pk_fma_f32 v[154:155], v[8:9], v[122:123], v[154:155]
	v_pk_fma_f32 v[156:157], v[10:11], v[124:125], v[156:157]
	v_pk_fma_f32 v[158:159], v[4:5], v[126:127], v[158:159]
	v_pk_fma_f32 v[160:161], v[6:7], v[128:129], v[160:161]
	v_pk_mul_f32 v[154:155], v[154:155], v[146:147]
	v_pk_mul_f32 v[156:157], v[156:157], v[148:149]
	v_pk_mul_f32 v[158:159], v[158:159], v[150:151]
	v_pk_mul_f32 v[160:161], v[160:161], v[152:153]
	v_cvt_pk_bf16_f32 v166, v154, v155
	v_cvt_pk_bf16_f32 v167, v156, v157
	v_cvt_pk_bf16_f32 v168, v158, v159
	v_cvt_pk_bf16_f32 v169, v160, v161
	global_store_dwordx4 v[54:55], v[166:169], off offset:2048 nt
	s_andn2_b64 exec, exec, s[30:31]
	s_cbranch_execz .LBB0_151

.LBB0_380:
	s_lshl_b32 s5, s5, 8
	s_lshl_b32 s6, s6, 7
	s_add_i32 s5, s5, s6
	v_add_u32_e32 v130, s5, v222
	v_ashrrev_i32_e32 v131, 31, v130
	v_lshlrev_b64 v[132:133], 6, v[130:131]
	v_lshl_add_u64 v[132:133], v[204:205], 0, v[132:133]
	global_load_dwordx4 v[136:139], v[132:133], off
	global_load_dwordx4 v[140:143], v[132:133], off offset:1024
	global_load_dwordx4 v[144:147], v[132:133], off offset:2048
	global_load_dwordx4 v[148:151], v[132:133], off offset:3072
	v_add_u32_e32 v168, 0x80, v130
	v_ashrrev_i32_e32 v169, 31, v168
	v_lshlrev_b64 v[168:169], 6, v[168:169]
	v_lshl_add_u64 v[168:169], v[204:205], 0, v[168:169]
	global_load_dwordx4 v[152:155], v[168:169], off
	global_load_dwordx4 v[156:159], v[168:169], off offset:1024
	global_load_dwordx4 v[160:163], v[168:169], off offset:2048
	global_load_dwordx4 v[164:167], v[168:169], off offset:3072
	s_lshl_b32 s4, s4, 7
	s_ashr_i32 s5, s4, 31
	s_lshl_b64 s[38:39], s[4:5], 1
	s_waitcnt vmcnt(7)
	v_add_f32_e32 v131, v136, v137
	v_add_f32_e32 v132, v138, v139
	v_add_f32_e32 v131, v131, v132
	v_mov_b32_e32 v132, v131
	s_nop 1
	v_permlane16_swap_b32_e32 v131, v132
	v_add_f32_e32 v131, v131, v132
	v_mov_b32_e32 v132, v131
	s_nop 1
	v_permlane32_swap_b32_e32 v131, v132
	v_add_f32_e32 v131, v131, v132
	v_fmamk_f32 v131, v131, 0x3a800000, v225
	v_cmp_gt_f32_e32 vcc, s3, v131
	v_mul_f32_e32 v132, 0x4b800000, v131
	s_nop 0
	v_cndmask_b32_e32 v131, v131, v132, vcc
	v_rsq_f32_e32 v131, v131
	s_nop 0
	v_mul_f32_e32 v132, 0x45800000, v131
	v_cndmask_b32_e32 v132, v131, v132, vcc
	v_pk_mul_f32 v[126:127], v[126:127], v[132:133] op_sel_hi:[1,0]
	v_pk_mul_f32 v[122:123], v[122:123], v[132:133] op_sel_hi:[1,0]
	v_mul_f32_e32 v131, 0xbfb8aa3b, v126
	v_exp_f32_e32 v131, v131
	v_pk_mul_f32 v[124:125], v[124:125], v[132:133] op_sel_hi:[1,0]
	v_pk_mul_f32 v[118:119], v[118:119], v[132:133] op_sel_hi:[1,0]
	v_pk_mul_f32 v[114:115], v[114:115], v[132:133] op_sel_hi:[1,0]
	v_add_f32_e32 v131, 1.0, v131
	v_rcp_f32_e32 v134, v131
	v_mul_f32_e32 v131, 0xbfb8aa3b, v127
	v_exp_f32_e32 v131, v131
	v_pk_mul_f32 v[116:117], v[116:117], v[132:133] op_sel_hi:[1,0]
	v_add_f32_e32 v131, 1.0, v131
	v_rcp_f32_e32 v135, v131
	s_nop 0
	v_pk_mul_f32 v[126:127], v[126:127], v[134:135]
	s_nop 0
	v_pk_mul_f32 v[122:123], v[122:123], v[126:127]
	v_pk_mul_f32 v[126:127], v[128:129], v[132:133] op_sel_hi:[1,0]
	s_nop 0
	v_mul_f32_e32 v128, 0xbfb8aa3b, v126
	v_mul_f32_e32 v129, 0xbfb8aa3b, v127
	v_exp_f32_e32 v128, v128
	v_exp_f32_e32 v129, v129
	v_add_f32_e32 v128, 1.0, v128
	v_add_f32_e32 v129, 1.0, v129
	v_rcp_f32_e32 v128, v128
	v_rcp_f32_e32 v129, v129
	s_nop 0
	v_pk_mul_f32 v[126:127], v[126:127], v[128:129]
	s_nop 0
	v_pk_mul_f32 v[124:125], v[124:125], v[126:127]
	v_mul_f32_e32 v126, 0xbfb8aa3b, v118
	v_mul_f32_e32 v127, 0xbfb8aa3b, v119
	v_exp_f32_e32 v126, v126
	v_exp_f32_e32 v127, v127
	v_add_f32_e32 v126, 1.0, v126
	v_add_f32_e32 v127, 1.0, v127
	v_rcp_f32_e32 v126, v126
	v_rcp_f32_e32 v127, v127
	s_nop 0
	v_pk_mul_f32 v[118:119], v[118:119], v[126:127]
	s_nop 0
	v_pk_mul_f32 v[118:119], v[114:115], v[118:119]
	v_pk_mul_f32 v[114:115], v[120:121], v[132:133] op_sel_hi:[1,0]
	s_nop 0
	v_mul_f32_e32 v120, 0xbfb8aa3b, v114
	v_mul_f32_e32 v121, 0xbfb8aa3b, v115
	v_exp_f32_e32 v120, v120
	v_exp_f32_e32 v121, v121
	v_add_f32_e32 v120, 1.0, v120
	v_add_f32_e32 v121, 1.0, v121
	v_rcp_f32_e32 v120, v120
	v_rcp_f32_e32 v121, v121
	s_nop 0
	v_pk_mul_f32 v[114:115], v[114:115], v[120:121]
	s_nop 0
	v_pk_mul_f32 v[120:121], v[116:117], v[114:115]
	v_cvt_pk_bf16_f32 v116, v118, v119
	v_mov_b64_e32 v[118:119], s[62:63]
	v_cvt_pk_bf16_f32 v117, v120, v121
	v_mad_i64_i32 v[120:121], s[6:7], v130, s16, v[118:119]
	v_lshl_add_u64 v[120:121], v[120:121], 0, s[38:39]
	v_lshl_add_u64 v[120:121], v[120:121], 0, s[68:69]
	v_cvt_pk_bf16_f32 v114, v122, v123
	v_cvt_pk_bf16_f32 v115, v124, v125
	v_lshl_add_u64 v[120:121], v[120:121], 0, v[96:97]
	global_store_dwordx4 v[120:121], v[114:117], off nt
	s_nop 1
	v_or_b32_e32 v114, 16, v130
	v_ashrrev_i32_e32 v115, 31, v114
	v_lshlrev_b64 v[116:117], 6, v[114:115]
	v_lshl_add_u64 v[116:117], v[204:205], 0, v[116:117]
	s_waitcnt vmcnt(7)
	v_add_f32_e32 v115, v140, v141
	v_add_f32_e32 v116, v142, v143
	v_add_f32_e32 v115, v115, v116
	v_mov_b32_e32 v116, v115
	s_nop 1
	v_permlane16_swap_b32_e32 v115, v116
	v_add_f32_e32 v115, v115, v116
	v_mov_b32_e32 v116, v115
	s_nop 1
	v_permlane32_swap_b32_e32 v115, v116
	v_add_f32_e32 v115, v115, v116
	v_fmamk_f32 v115, v115, 0x3a800000, v225
	v_cmp_gt_f32_e32 vcc, s3, v115
	v_mul_f32_e32 v116, 0x4b800000, v115
	s_nop 0
	v_cndmask_b32_e32 v115, v115, v116, vcc
	v_rsq_f32_e32 v115, v115
	s_nop 0
	v_mul_f32_e32 v116, 0x45800000, v115
	v_cndmask_b32_e32 v116, v115, v116, vcc
	v_pk_mul_f32 v[110:111], v[110:111], v[116:117] op_sel_hi:[1,0]
	v_pk_mul_f32 v[106:107], v[106:107], v[116:117] op_sel_hi:[1,0]
	v_mul_f32_e32 v115, 0xbfb8aa3b, v110
	v_exp_f32_e32 v115, v115
	v_pk_mul_f32 v[108:109], v[108:109], v[116:117] op_sel_hi:[1,0]
	v_pk_mul_f32 v[102:103], v[102:103], v[116:117] op_sel_hi:[1,0]
	v_pk_mul_f32 v[98:99], v[98:99], v[116:117] op_sel_hi:[1,0]
	v_add_f32_e32 v115, 1.0, v115
	v_rcp_f32_e32 v120, v115
	v_mul_f32_e32 v115, 0xbfb8aa3b, v111
	v_exp_f32_e32 v115, v115
	v_pk_mul_f32 v[100:101], v[100:101], v[116:117] op_sel_hi:[1,0]
	v_add_f32_e32 v115, 1.0, v115
	v_rcp_f32_e32 v121, v115
	s_nop 0
	v_pk_mul_f32 v[110:111], v[110:111], v[120:121]
	s_nop 0
	v_pk_mul_f32 v[106:107], v[106:107], v[110:111]
	v_pk_mul_f32 v[110:111], v[112:113], v[116:117] op_sel_hi:[1,0]
	s_nop 0
	v_mul_f32_e32 v112, 0xbfb8aa3b, v110
	v_mul_f32_e32 v113, 0xbfb8aa3b, v111
	v_exp_f32_e32 v112, v112
	v_exp_f32_e32 v113, v113
	v_add_f32_e32 v112, 1.0, v112
	v_add_f32_e32 v113, 1.0, v113
	v_rcp_f32_e32 v112, v112
	v_rcp_f32_e32 v113, v113
	s_nop 0
	v_pk_mul_f32 v[110:111], v[110:111], v[112:113]
	s_nop 0
	v_pk_mul_f32 v[108:109], v[108:109], v[110:111]
	v_mul_f32_e32 v110, 0xbfb8aa3b, v102
	v_mul_f32_e32 v111, 0xbfb8aa3b, v103
	v_exp_f32_e32 v110, v110
	v_exp_f32_e32 v111, v111
	v_add_f32_e32 v110, 1.0, v110
	v_add_f32_e32 v111, 1.0, v111
	v_rcp_f32_e32 v110, v110
	v_rcp_f32_e32 v111, v111
	s_nop 0
	v_pk_mul_f32 v[102:103], v[102:103], v[110:111]
	s_nop 0
	v_pk_mul_f32 v[102:103], v[98:99], v[102:103]
	v_pk_mul_f32 v[98:99], v[104:105], v[116:117] op_sel_hi:[1,0]
	s_nop 0
	v_mul_f32_e32 v104, 0xbfb8aa3b, v98
	v_mul_f32_e32 v105, 0xbfb8aa3b, v99
	v_exp_f32_e32 v104, v104
	v_exp_f32_e32 v105, v105
	v_add_f32_e32 v104, 1.0, v104
	v_add_f32_e32 v105, 1.0, v105
	v_rcp_f32_e32 v104, v104
	v_rcp_f32_e32 v105, v105
	s_nop 0
	v_pk_mul_f32 v[98:99], v[98:99], v[104:105]
	s_nop 0
	v_pk_mul_f32 v[104:105], v[100:101], v[98:99]
	v_cvt_pk_bf16_f32 v100, v102, v103
	v_mad_i64_i32 v[102:103], s[4:5], v114, s16, v[118:119]
	v_lshl_add_u64 v[102:103], v[102:103], 0, s[38:39]
	v_lshl_add_u64 v[102:103], v[102:103], 0, s[68:69]
	v_cvt_pk_bf16_f32 v98, v106, v107
	v_cvt_pk_bf16_f32 v99, v108, v109
	v_cvt_pk_bf16_f32 v101, v104, v105
	v_lshl_add_u64 v[102:103], v[102:103], 0, v[96:97]
	global_store_dwordx4 v[102:103], v[98:101], off nt
	s_nop 1
	v_or_b32_e32 v98, 32, v130
	v_ashrrev_i32_e32 v99, 31, v98
	v_lshlrev_b64 v[100:101], 6, v[98:99]
	v_lshl_add_u64 v[100:101], v[204:205], 0, v[100:101]
	s_waitcnt vmcnt(7)
	v_add_f32_e32 v99, v144, v145
	v_add_f32_e32 v100, v146, v147
	v_add_f32_e32 v99, v99, v100
	v_mov_b32_e32 v100, v99
	s_nop 1
	v_permlane16_swap_b32_e32 v99, v100
	v_add_f32_e32 v99, v99, v100
	v_mov_b32_e32 v100, v99
	s_nop 1
	v_permlane32_swap_b32_e32 v99, v100
	v_add_f32_e32 v99, v99, v100
	v_fmamk_f32 v99, v99, 0x3a800000, v225
	v_cmp_gt_f32_e32 vcc, s3, v99
	v_mul_f32_e32 v100, 0x4b800000, v99
	s_nop 0
	v_cndmask_b32_e32 v99, v99, v100, vcc
	v_rsq_f32_e32 v99, v99
	s_nop 0
	v_mul_f32_e32 v100, 0x45800000, v99
	v_cndmask_b32_e32 v100, v99, v100, vcc
	v_pk_mul_f32 v[92:93], v[92:93], v[100:101] op_sel_hi:[1,0]
	v_pk_mul_f32 v[88:89], v[88:89], v[100:101] op_sel_hi:[1,0]
	v_mul_f32_e32 v99, 0xbfb8aa3b, v92
	v_exp_f32_e32 v99, v99
	v_pk_mul_f32 v[90:91], v[90:91], v[100:101] op_sel_hi:[1,0]
	v_pk_mul_f32 v[84:85], v[84:85], v[100:101] op_sel_hi:[1,0]
	v_pk_mul_f32 v[80:81], v[80:81], v[100:101] op_sel_hi:[1,0]
	v_add_f32_e32 v99, 1.0, v99
	v_rcp_f32_e32 v102, v99
	v_mul_f32_e32 v99, 0xbfb8aa3b, v93
	v_exp_f32_e32 v99, v99
	v_pk_mul_f32 v[82:83], v[82:83], v[100:101] op_sel_hi:[1,0]
	v_add_f32_e32 v99, 1.0, v99
	v_rcp_f32_e32 v103, v99
	s_nop 0
	v_pk_mul_f32 v[92:93], v[92:93], v[102:103]
	s_nop 0
	v_pk_mul_f32 v[88:89], v[88:89], v[92:93]
	v_pk_mul_f32 v[92:93], v[94:95], v[100:101] op_sel_hi:[1,0]
	s_nop 0
	v_mul_f32_e32 v94, 0xbfb8aa3b, v92
	v_mul_f32_e32 v95, 0xbfb8aa3b, v93
	v_exp_f32_e32 v94, v94
	v_exp_f32_e32 v95, v95
	v_add_f32_e32 v94, 1.0, v94
	v_add_f32_e32 v95, 1.0, v95
	v_rcp_f32_e32 v94, v94
	v_rcp_f32_e32 v95, v95
	s_nop 0
	v_pk_mul_f32 v[92:93], v[92:93], v[94:95]
	s_nop 0
	v_pk_mul_f32 v[90:91], v[90:91], v[92:93]
	v_mul_f32_e32 v92, 0xbfb8aa3b, v84
	v_mul_f32_e32 v93, 0xbfb8aa3b, v85
	v_exp_f32_e32 v92, v92
	v_exp_f32_e32 v93, v93
	v_add_f32_e32 v92, 1.0, v92
	v_add_f32_e32 v93, 1.0, v93
	v_rcp_f32_e32 v92, v92
	v_rcp_f32_e32 v93, v93
	s_nop 0
	v_pk_mul_f32 v[84:85], v[84:85], v[92:93]
	s_nop 0
	v_pk_mul_f32 v[84:85], v[80:81], v[84:85]
	v_pk_mul_f32 v[80:81], v[86:87], v[100:101] op_sel_hi:[1,0]
	s_nop 0
	v_mul_f32_e32 v86, 0xbfb8aa3b, v80
	v_mul_f32_e32 v87, 0xbfb8aa3b, v81
	v_exp_f32_e32 v86, v86
	v_exp_f32_e32 v87, v87
	v_add_f32_e32 v86, 1.0, v86
	v_add_f32_e32 v87, 1.0, v87
	v_rcp_f32_e32 v86, v86
	v_rcp_f32_e32 v87, v87
	s_nop 0
	v_pk_mul_f32 v[80:81], v[80:81], v[86:87]
	s_nop 0
	v_pk_mul_f32 v[86:87], v[82:83], v[80:81]
	v_cvt_pk_bf16_f32 v82, v84, v85
	v_mad_i64_i32 v[84:85], s[4:5], v98, s16, v[118:119]
	v_lshl_add_u64 v[84:85], v[84:85], 0, s[38:39]
	v_lshl_add_u64 v[84:85], v[84:85], 0, s[68:69]
	v_cvt_pk_bf16_f32 v80, v88, v89
	v_cvt_pk_bf16_f32 v81, v90, v91
	v_cvt_pk_bf16_f32 v83, v86, v87
	v_lshl_add_u64 v[84:85], v[84:85], 0, v[96:97]
	global_store_dwordx4 v[84:85], v[80:83], off nt
	s_nop 1
	v_or_b32_e32 v80, 48, v130
	v_ashrrev_i32_e32 v81, 31, v80
	v_lshlrev_b64 v[82:83], 6, v[80:81]
	v_lshl_add_u64 v[82:83], v[204:205], 0, v[82:83]
	s_waitcnt vmcnt(7)
	v_add_f32_e32 v81, v148, v149
	v_add_f32_e32 v82, v150, v151
	v_add_f32_e32 v81, v81, v82
	v_mov_b32_e32 v82, v81
	s_nop 1
	v_permlane16_swap_b32_e32 v81, v82
	v_add_f32_e32 v81, v81, v82
	v_mov_b32_e32 v82, v81
	s_nop 1
	v_permlane32_swap_b32_e32 v81, v82
	v_add_f32_e32 v81, v81, v82
	v_fmamk_f32 v81, v81, 0x3a800000, v225
	v_cmp_gt_f32_e32 vcc, s3, v81
	v_mul_f32_e32 v82, 0x4b800000, v81
	s_nop 0
	v_cndmask_b32_e32 v81, v81, v82, vcc
	v_rsq_f32_e32 v81, v81
	s_nop 0
	v_mul_f32_e32 v82, 0x45800000, v81
	v_cndmask_b32_e32 v82, v81, v82, vcc
	v_pk_mul_f32 v[76:77], v[76:77], v[82:83] op_sel_hi:[1,0]
	v_pk_mul_f32 v[72:73], v[72:73], v[82:83] op_sel_hi:[1,0]
	v_mul_f32_e32 v81, 0xbfb8aa3b, v76
	v_exp_f32_e32 v81, v81
	v_pk_mul_f32 v[74:75], v[74:75], v[82:83] op_sel_hi:[1,0]
	v_pk_mul_f32 v[68:69], v[68:69], v[82:83] op_sel_hi:[1,0]
	v_pk_mul_f32 v[64:65], v[64:65], v[82:83] op_sel_hi:[1,0]
	v_add_f32_e32 v81, 1.0, v81
	v_rcp_f32_e32 v84, v81
	v_mul_f32_e32 v81, 0xbfb8aa3b, v77
	v_exp_f32_e32 v81, v81
	v_pk_mul_f32 v[66:67], v[66:67], v[82:83] op_sel_hi:[1,0]
	v_cmp_ne_u32_e32 vcc, 0, v247
	s_and_b64 vcc, exec, vcc
	v_add_f32_e32 v81, 1.0, v81
	v_rcp_f32_e32 v85, v81
	s_nop 0
	v_pk_mul_f32 v[76:77], v[76:77], v[84:85]
	s_nop 0
	v_pk_mul_f32 v[72:73], v[72:73], v[76:77]
	v_pk_mul_f32 v[76:77], v[78:79], v[82:83] op_sel_hi:[1,0]
	s_nop 0
	v_mul_f32_e32 v78, 0xbfb8aa3b, v76
	v_mul_f32_e32 v79, 0xbfb8aa3b, v77
	v_exp_f32_e32 v78, v78
	v_exp_f32_e32 v79, v79
	v_add_f32_e32 v78, 1.0, v78
	v_add_f32_e32 v79, 1.0, v79
	v_rcp_f32_e32 v78, v78
	v_rcp_f32_e32 v79, v79
	s_nop 0
	v_pk_mul_f32 v[76:77], v[76:77], v[78:79]
	s_nop 0
	v_pk_mul_f32 v[74:75], v[74:75], v[76:77]
	v_mul_f32_e32 v76, 0xbfb8aa3b, v68
	v_mul_f32_e32 v77, 0xbfb8aa3b, v69
	v_exp_f32_e32 v76, v76
	v_exp_f32_e32 v77, v77
	v_add_f32_e32 v76, 1.0, v76
	v_add_f32_e32 v77, 1.0, v77
	v_rcp_f32_e32 v76, v76
	v_rcp_f32_e32 v77, v77
	s_nop 0
	v_pk_mul_f32 v[68:69], v[68:69], v[76:77]
	s_nop 0
	v_pk_mul_f32 v[68:69], v[64:65], v[68:69]
	v_pk_mul_f32 v[64:65], v[70:71], v[82:83] op_sel_hi:[1,0]
	s_nop 0
	v_mul_f32_e32 v70, 0xbfb8aa3b, v64
	v_mul_f32_e32 v71, 0xbfb8aa3b, v65
	v_exp_f32_e32 v70, v70
	v_exp_f32_e32 v71, v71
	v_add_f32_e32 v70, 1.0, v70
	v_add_f32_e32 v71, 1.0, v71
	v_rcp_f32_e32 v70, v70
	v_rcp_f32_e32 v71, v71
	s_nop 0
	v_pk_mul_f32 v[64:65], v[64:65], v[70:71]
	s_nop 0
	v_pk_mul_f32 v[70:71], v[66:67], v[64:65]
	v_cvt_pk_bf16_f32 v66, v68, v69
	v_mad_i64_i32 v[68:69], s[4:5], v80, s16, v[118:119]
	v_lshl_add_u64 v[68:69], v[68:69], 0, s[38:39]
	v_lshl_add_u64 v[68:69], v[68:69], 0, s[68:69]
	v_cvt_pk_bf16_f32 v64, v72, v73
	v_cvt_pk_bf16_f32 v65, v74, v75
	v_cvt_pk_bf16_f32 v67, v70, v71
	v_lshl_add_u64 v[68:69], v[68:69], 0, v[96:97]
	global_store_dwordx4 v[68:69], v[64:67], off nt
	s_cbranch_vccz .LBB0_382
	s_waitcnt vmcnt(4)
	s_and_b64 vcc, exec, s[36:37]
	s_mov_b64 s[30:31], -1
	s_cbranch_vccnz .LBB0_349
	s_branch .LBB0_383
.LBB0_382:
	s_nop 0
	v_add_u32_e32 v64, 0x80, v130
	v_ashrrev_i32_e32 v65, 31, v64
	v_lshlrev_b64 v[66:67], 6, v[64:65]
	v_lshl_add_u64 v[66:67], v[204:205], 0, v[66:67]
	s_waitcnt vmcnt(7)
	v_add_f32_e32 v65, v152, v153
	v_add_f32_e32 v66, v154, v155
	v_add_f32_e32 v65, v65, v66
	v_mov_b32_e32 v66, v65
	s_nop 1
	v_permlane16_swap_b32_e32 v65, v66
	v_add_f32_e32 v65, v65, v66
	v_mov_b32_e32 v66, v65
	s_nop 1
	v_permlane32_swap_b32_e32 v65, v66
	v_add_f32_e32 v65, v65, v66
	v_fmamk_f32 v65, v65, 0x3a800000, v225
	v_cmp_gt_f32_e32 vcc, s3, v65
	v_mul_f32_e32 v66, 0x4b800000, v65
	s_nop 0
	v_cndmask_b32_e32 v65, v65, v66, vcc
	v_rsq_f32_e32 v65, v65
	s_nop 0
	v_mul_f32_e32 v66, 0x45800000, v65
	v_cndmask_b32_e32 v66, v65, v66, vcc
	v_pk_mul_f32 v[48:49], v[48:49], v[66:67] op_sel_hi:[1,0]
	v_pk_mul_f32 v[60:61], v[60:61], v[66:67] op_sel_hi:[1,0]
	v_mul_f32_e32 v65, 0xbfb8aa3b, v48
	v_exp_f32_e32 v65, v65
	v_pk_mul_f32 v[50:51], v[50:51], v[66:67] op_sel_hi:[1,0]
	v_pk_mul_f32 v[56:57], v[56:57], v[66:67] op_sel_hi:[1,0]
	v_pk_mul_f32 v[52:53], v[52:53], v[66:67] op_sel_hi:[1,0]
	v_add_f32_e32 v65, 1.0, v65
	v_rcp_f32_e32 v68, v65
	v_mul_f32_e32 v65, 0xbfb8aa3b, v49
	v_exp_f32_e32 v65, v65
	v_pk_mul_f32 v[62:63], v[62:63], v[66:67] op_sel_hi:[1,0]
	v_pk_mul_f32 v[54:55], v[54:55], v[66:67] op_sel_hi:[1,0]
	v_add_f32_e32 v65, 1.0, v65
	v_rcp_f32_e32 v69, v65
	s_nop 0
	v_pk_mul_f32 v[48:49], v[48:49], v[68:69]
	s_nop 0
	v_pk_mul_f32 v[48:49], v[60:61], v[48:49]
	v_mul_f32_e32 v60, 0xbfb8aa3b, v50
	v_mul_f32_e32 v61, 0xbfb8aa3b, v51
	v_exp_f32_e32 v60, v60
	v_exp_f32_e32 v61, v61
	v_cvt_pk_bf16_f32 v48, v48, v49
	v_add_f32_e32 v60, 1.0, v60
	v_add_f32_e32 v61, 1.0, v61
	v_rcp_f32_e32 v60, v60
	v_rcp_f32_e32 v61, v61
	s_nop 0
	v_pk_mul_f32 v[50:51], v[50:51], v[60:61]
	v_mul_f32_e32 v60, 0xbfb8aa3b, v56
	v_mul_f32_e32 v61, 0xbfb8aa3b, v57
	v_exp_f32_e32 v60, v60
	v_exp_f32_e32 v61, v61
	v_pk_mul_f32 v[50:51], v[62:63], v[50:51]
	v_add_f32_e32 v60, 1.0, v60
	v_add_f32_e32 v61, 1.0, v61
	v_rcp_f32_e32 v60, v60
	v_rcp_f32_e32 v61, v61
	v_cvt_pk_bf16_f32 v49, v50, v51
	v_pk_mul_f32 v[56:57], v[56:57], v[60:61]
	s_nop 0
	v_pk_mul_f32 v[52:53], v[52:53], v[56:57]
	v_pk_mul_f32 v[56:57], v[58:59], v[66:67] op_sel_hi:[1,0]
	v_cvt_pk_bf16_f32 v50, v52, v53
	v_mul_f32_e32 v58, 0xbfb8aa3b, v56
	v_mul_f32_e32 v59, 0xbfb8aa3b, v57
	v_exp_f32_e32 v58, v58
	v_exp_f32_e32 v59, v59
	v_mov_b64_e32 v[52:53], s[62:63]
	v_add_f32_e32 v58, 1.0, v58
	v_add_f32_e32 v59, 1.0, v59
	v_rcp_f32_e32 v58, v58
	v_rcp_f32_e32 v59, v59
	s_nop 0
	v_pk_mul_f32 v[56:57], v[56:57], v[58:59]
	s_nop 0
	v_pk_mul_f32 v[54:55], v[54:55], v[56:57]
	s_nop 0
	v_cvt_pk_bf16_f32 v51, v54, v55
	v_mad_i64_i32 v[54:55], s[4:5], v64, s16, v[52:53]
	v_lshl_add_u64 v[54:55], v[54:55], 0, s[38:39]
	v_lshl_add_u64 v[54:55], v[54:55], 0, s[68:69]
	v_lshl_add_u64 v[54:55], v[54:55], 0, v[96:97]
	global_store_dwordx4 v[54:55], v[48:51], off nt
	s_nop 1
	v_add_u32_e32 v48, 0x90, v130
	v_ashrrev_i32_e32 v49, 31, v48
	v_lshlrev_b64 v[50:51], 6, v[48:49]
	v_lshl_add_u64 v[50:51], v[204:205], 0, v[50:51]
	s_waitcnt vmcnt(7)
	v_add_f32_e32 v49, v156, v157
	v_add_f32_e32 v50, v158, v159
	v_add_f32_e32 v49, v49, v50
	v_mov_b32_e32 v50, v49
	s_nop 1
	v_permlane16_swap_b32_e32 v49, v50
	v_add_f32_e32 v49, v49, v50
	v_mov_b32_e32 v50, v49
	s_nop 1
	v_permlane32_swap_b32_e32 v49, v50
	v_add_f32_e32 v49, v49, v50
	v_fmamk_f32 v49, v49, 0x3a800000, v225
	v_cmp_gt_f32_e32 vcc, s3, v49
	v_mul_f32_e32 v50, 0x4b800000, v49
	s_nop 0
	v_cndmask_b32_e32 v49, v49, v50, vcc
	v_rsq_f32_e32 v49, v49
	s_nop 0
	v_mul_f32_e32 v50, 0x45800000, v49
	v_cndmask_b32_e32 v50, v49, v50, vcc
	v_pk_mul_f32 v[44:45], v[44:45], v[50:51] op_sel_hi:[1,0]
	v_pk_mul_f32 v[40:41], v[40:41], v[50:51] op_sel_hi:[1,0]
	v_mul_f32_e32 v49, 0xbfb8aa3b, v44
	v_exp_f32_e32 v49, v49
	v_pk_mul_f32 v[42:43], v[42:43], v[50:51] op_sel_hi:[1,0]
	v_pk_mul_f32 v[36:37], v[36:37], v[50:51] op_sel_hi:[1,0]
	v_pk_mul_f32 v[32:33], v[32:33], v[50:51] op_sel_hi:[1,0]
	v_add_f32_e32 v49, 1.0, v49
	v_rcp_f32_e32 v54, v49
	v_mul_f32_e32 v49, 0xbfb8aa3b, v45
	v_exp_f32_e32 v49, v49
	v_pk_mul_f32 v[34:35], v[34:35], v[50:51] op_sel_hi:[1,0]
	v_add_f32_e32 v49, 1.0, v49
	v_rcp_f32_e32 v55, v49
	s_nop 0
	v_pk_mul_f32 v[44:45], v[44:45], v[54:55]
	s_nop 0
	v_pk_mul_f32 v[40:41], v[40:41], v[44:45]
	v_pk_mul_f32 v[44:45], v[46:47], v[50:51] op_sel_hi:[1,0]
	s_nop 0
	v_mul_f32_e32 v46, 0xbfb8aa3b, v44
	v_mul_f32_e32 v47, 0xbfb8aa3b, v45
	v_exp_f32_e32 v46, v46
	v_exp_f32_e32 v47, v47
	v_add_f32_e32 v46, 1.0, v46
	v_add_f32_e32 v47, 1.0, v47
	v_rcp_f32_e32 v46, v46
	v_rcp_f32_e32 v47, v47
	s_nop 0
	v_pk_mul_f32 v[44:45], v[44:45], v[46:47]
	s_nop 0
	v_pk_mul_f32 v[42:43], v[42:43], v[44:45]
	v_mul_f32_e32 v44, 0xbfb8aa3b, v36
	v_mul_f32_e32 v45, 0xbfb8aa3b, v37
	v_exp_f32_e32 v44, v44
	v_exp_f32_e32 v45, v45
	v_add_f32_e32 v44, 1.0, v44
	v_add_f32_e32 v45, 1.0, v45
	v_rcp_f32_e32 v44, v44
	v_rcp_f32_e32 v45, v45
	s_nop 0
	v_pk_mul_f32 v[36:37], v[36:37], v[44:45]
	s_nop 0
	v_pk_mul_f32 v[36:37], v[32:33], v[36:37]
	v_pk_mul_f32 v[32:33], v[38:39], v[50:51] op_sel_hi:[1,0]
	s_nop 0
	v_mul_f32_e32 v38, 0xbfb8aa3b, v32
	v_mul_f32_e32 v39, 0xbfb8aa3b, v33
	v_exp_f32_e32 v38, v38
	v_exp_f32_e32 v39, v39
	v_add_f32_e32 v38, 1.0, v38
	v_add_f32_e32 v39, 1.0, v39
	v_rcp_f32_e32 v38, v38
	v_rcp_f32_e32 v39, v39
	s_nop 0
	v_pk_mul_f32 v[32:33], v[32:33], v[38:39]
	s_nop 0
	v_pk_mul_f32 v[38:39], v[34:35], v[32:33]
	v_cvt_pk_bf16_f32 v34, v36, v37
	v_mad_i64_i32 v[36:37], s[4:5], v48, s16, v[52:53]
	v_lshl_add_u64 v[36:37], v[36:37], 0, s[38:39]
	v_lshl_add_u64 v[36:37], v[36:37], 0, s[68:69]
	v_cvt_pk_bf16_f32 v32, v40, v41
	v_cvt_pk_bf16_f32 v33, v42, v43
	v_cvt_pk_bf16_f32 v35, v38, v39
	v_lshl_add_u64 v[36:37], v[36:37], 0, v[96:97]
	global_store_dwordx4 v[36:37], v[32:35], off nt
	s_nop 1
	v_add_u32_e32 v32, 0xa0, v130
	v_ashrrev_i32_e32 v33, 31, v32
	v_lshlrev_b64 v[34:35], 6, v[32:33]
	v_lshl_add_u64 v[34:35], v[204:205], 0, v[34:35]
	s_waitcnt vmcnt(7)
	v_add_f32_e32 v33, v160, v161
	v_add_f32_e32 v34, v162, v163
	v_add_f32_e32 v33, v33, v34
	v_mov_b32_e32 v34, v33
	s_nop 1
	v_permlane16_swap_b32_e32 v33, v34
	v_add_f32_e32 v33, v33, v34
	v_mov_b32_e32 v34, v33
	s_nop 1
	v_permlane32_swap_b32_e32 v33, v34
	v_add_f32_e32 v33, v33, v34
	v_fmamk_f32 v33, v33, 0x3a800000, v225
	v_cmp_gt_f32_e32 vcc, s3, v33
	v_mul_f32_e32 v34, 0x4b800000, v33
	s_nop 0
	v_cndmask_b32_e32 v33, v33, v34, vcc
	v_rsq_f32_e32 v33, v33
	s_nop 0
	v_mul_f32_e32 v34, 0x45800000, v33
	v_cndmask_b32_e32 v34, v33, v34, vcc
	v_pk_mul_f32 v[28:29], v[28:29], v[34:35] op_sel_hi:[1,0]
	v_pk_mul_f32 v[24:25], v[24:25], v[34:35] op_sel_hi:[1,0]
	v_mul_f32_e32 v33, 0xbfb8aa3b, v28
	v_exp_f32_e32 v33, v33
	v_pk_mul_f32 v[26:27], v[26:27], v[34:35] op_sel_hi:[1,0]
	v_pk_mul_f32 v[20:21], v[20:21], v[34:35] op_sel_hi:[1,0]
	v_pk_mul_f32 v[16:17], v[16:17], v[34:35] op_sel_hi:[1,0]
	v_add_f32_e32 v33, 1.0, v33
	v_rcp_f32_e32 v36, v33
	v_mul_f32_e32 v33, 0xbfb8aa3b, v29
	v_exp_f32_e32 v33, v33
	v_pk_mul_f32 v[18:19], v[18:19], v[34:35] op_sel_hi:[1,0]
	v_add_f32_e32 v33, 1.0, v33
	v_rcp_f32_e32 v37, v33
	s_nop 0
	v_pk_mul_f32 v[28:29], v[28:29], v[36:37]
	s_nop 0
	v_pk_mul_f32 v[24:25], v[24:25], v[28:29]
	v_pk_mul_f32 v[28:29], v[30:31], v[34:35] op_sel_hi:[1,0]
	s_nop 0
	v_mul_f32_e32 v30, 0xbfb8aa3b, v28
	v_mul_f32_e32 v31, 0xbfb8aa3b, v29
	v_exp_f32_e32 v30, v30
	v_exp_f32_e32 v31, v31
	v_add_f32_e32 v30, 1.0, v30
	v_add_f32_e32 v31, 1.0, v31
	v_rcp_f32_e32 v30, v30
	v_rcp_f32_e32 v31, v31
	s_nop 0
	v_pk_mul_f32 v[28:29], v[28:29], v[30:31]
	s_nop 0
	v_pk_mul_f32 v[26:27], v[26:27], v[28:29]
	v_mul_f32_e32 v28, 0xbfb8aa3b, v20
	v_mul_f32_e32 v29, 0xbfb8aa3b, v21
	v_exp_f32_e32 v28, v28
	v_exp_f32_e32 v29, v29
	v_add_f32_e32 v28, 1.0, v28
	v_add_f32_e32 v29, 1.0, v29
	v_rcp_f32_e32 v28, v28
	v_rcp_f32_e32 v29, v29
	s_nop 0
	v_pk_mul_f32 v[20:21], v[20:21], v[28:29]
	s_nop 0
	v_pk_mul_f32 v[20:21], v[16:17], v[20:21]
	v_pk_mul_f32 v[16:17], v[22:23], v[34:35] op_sel_hi:[1,0]
	s_nop 0
	v_mul_f32_e32 v22, 0xbfb8aa3b, v16
	v_mul_f32_e32 v23, 0xbfb8aa3b, v17
	v_exp_f32_e32 v22, v22
	v_exp_f32_e32 v23, v23
	v_add_f32_e32 v22, 1.0, v22
	v_add_f32_e32 v23, 1.0, v23
	v_rcp_f32_e32 v22, v22
	v_rcp_f32_e32 v23, v23
	s_nop 0
	v_pk_mul_f32 v[16:17], v[16:17], v[22:23]
	s_nop 0
	v_pk_mul_f32 v[22:23], v[18:19], v[16:17]
	v_cvt_pk_bf16_f32 v18, v20, v21
	v_mad_i64_i32 v[20:21], s[4:5], v32, s16, v[52:53]
	v_lshl_add_u64 v[20:21], v[20:21], 0, s[38:39]
	v_lshl_add_u64 v[20:21], v[20:21], 0, s[68:69]
	v_cvt_pk_bf16_f32 v16, v24, v25
	v_cvt_pk_bf16_f32 v17, v26, v27
	v_cvt_pk_bf16_f32 v19, v22, v23
	v_lshl_add_u64 v[20:21], v[20:21], 0, v[96:97]
	global_store_dwordx4 v[20:21], v[16:19], off nt
	s_nop 1
	v_add_u32_e32 v16, 0xb0, v130
	v_ashrrev_i32_e32 v17, 31, v16
	v_lshlrev_b64 v[18:19], 6, v[16:17]
	v_lshl_add_u64 v[18:19], v[204:205], 0, v[18:19]
	s_waitcnt vmcnt(7)
	v_add_f32_e32 v17, v164, v165
	v_add_f32_e32 v18, v166, v167
	v_add_f32_e32 v17, v17, v18
	v_mov_b32_e32 v18, v17
	s_nop 1
	v_permlane16_swap_b32_e32 v17, v18
	v_add_f32_e32 v17, v17, v18
	v_mov_b32_e32 v18, v17
	s_nop 1
	v_permlane32_swap_b32_e32 v17, v18
	v_add_f32_e32 v17, v17, v18
	v_fmamk_f32 v17, v17, 0x3a800000, v225
	v_cmp_gt_f32_e32 vcc, s3, v17
	v_mul_f32_e32 v18, 0x4b800000, v17
	s_nop 0
	v_cndmask_b32_e32 v17, v17, v18, vcc
	v_rsq_f32_e32 v17, v17
	s_nop 0
	v_mul_f32_e32 v18, 0x45800000, v17
	v_cndmask_b32_e32 v18, v17, v18, vcc
	v_pk_mul_f32 v[12:13], v[12:13], v[18:19] op_sel_hi:[1,0]
	v_pk_mul_f32 v[8:9], v[8:9], v[18:19] op_sel_hi:[1,0]
	v_mul_f32_e32 v17, 0xbfb8aa3b, v12
	v_exp_f32_e32 v17, v17
	v_pk_mul_f32 v[10:11], v[10:11], v[18:19] op_sel_hi:[1,0]
	v_pk_mul_f32 v[4:5], v[4:5], v[18:19] op_sel_hi:[1,0]
	v_pk_mul_f32 v[0:1], v[0:1], v[18:19] op_sel_hi:[1,0]
	v_add_f32_e32 v17, 1.0, v17
	v_rcp_f32_e32 v20, v17
	v_mul_f32_e32 v17, 0xbfb8aa3b, v13
	v_exp_f32_e32 v17, v17
	v_pk_mul_f32 v[2:3], v[2:3], v[18:19] op_sel_hi:[1,0]
	v_add_f32_e32 v17, 1.0, v17
	v_rcp_f32_e32 v21, v17
	s_nop 0
	v_pk_mul_f32 v[12:13], v[12:13], v[20:21]
	s_nop 0
	v_pk_mul_f32 v[8:9], v[8:9], v[12:13]
	v_pk_mul_f32 v[12:13], v[14:15], v[18:19] op_sel_hi:[1,0]
	s_nop 0
	v_mul_f32_e32 v14, 0xbfb8aa3b, v12
	v_mul_f32_e32 v15, 0xbfb8aa3b, v13
	v_exp_f32_e32 v14, v14
	v_exp_f32_e32 v15, v15
	v_add_f32_e32 v14, 1.0, v14
	v_add_f32_e32 v15, 1.0, v15
	v_rcp_f32_e32 v14, v14
	v_rcp_f32_e32 v15, v15
	s_nop 0
	v_pk_mul_f32 v[12:13], v[12:13], v[14:15]
	s_nop 0
	v_pk_mul_f32 v[10:11], v[10:11], v[12:13]
	v_mul_f32_e32 v12, 0xbfb8aa3b, v4
	v_mul_f32_e32 v13, 0xbfb8aa3b, v5
	v_exp_f32_e32 v12, v12
	v_exp_f32_e32 v13, v13
	v_add_f32_e32 v12, 1.0, v12
	v_add_f32_e32 v13, 1.0, v13
	v_rcp_f32_e32 v12, v12
	v_rcp_f32_e32 v13, v13
	s_nop 0
	v_pk_mul_f32 v[4:5], v[4:5], v[12:13]
	s_nop 0
	v_pk_mul_f32 v[4:5], v[0:1], v[4:5]
	v_pk_mul_f32 v[0:1], v[6:7], v[18:19] op_sel_hi:[1,0]
	s_nop 0
	v_mul_f32_e32 v6, 0xbfb8aa3b, v0
	v_mul_f32_e32 v7, 0xbfb8aa3b, v1
	v_exp_f32_e32 v6, v6
	v_exp_f32_e32 v7, v7
	v_add_f32_e32 v6, 1.0, v6
	v_add_f32_e32 v7, 1.0, v7
	v_rcp_f32_e32 v6, v6
	v_rcp_f32_e32 v7, v7
	s_nop 0
	v_pk_mul_f32 v[0:1], v[0:1], v[6:7]
	s_nop 0
	v_pk_mul_f32 v[6:7], v[2:3], v[0:1]
	v_cvt_pk_bf16_f32 v2, v4, v5
	v_mad_i64_i32 v[4:5], s[4:5], v16, s16, v[52:53]
	v_lshl_add_u64 v[4:5], v[4:5], 0, s[38:39]
	v_lshl_add_u64 v[4:5], v[4:5], 0, s[68:69]
	v_cvt_pk_bf16_f32 v0, v8, v9
	v_cvt_pk_bf16_f32 v1, v10, v11
	v_cvt_pk_bf16_f32 v3, v6, v7
	v_lshl_add_u64 v[4:5], v[4:5], 0, v[96:97]
	global_store_dwordx4 v[4:5], v[0:3], off nt
	s_and_b64 vcc, exec, s[36:37]
	s_mov_b64 s[30:31], -1
	s_cbranch_vccnz .LBB0_349

.LBB0_434:
	v_lshlrev_b64 v[98:99], 6, v[132:133]
	v_lshl_add_u64 v[98:99], v[206:207], 0, v[98:99]
	global_load_dwordx4 v[158:161], v[98:99], off
	global_load_dwordx4 v[162:165], v[98:99], off offset:1024
	global_load_dwordx4 v[166:169], v[98:99], off offset:2048
	global_load_dwordx4 v[170:173], v[98:99], off offset:3072
	v_add_u32_e32 v190, 0x80, v132
	v_ashrrev_i32_e32 v191, 31, v190
	v_lshlrev_b64 v[190:191], 6, v[190:191]
	v_lshl_add_u64 v[190:191], v[206:207], 0, v[190:191]
	global_load_dwordx4 v[174:177], v[190:191], off
	global_load_dwordx4 v[178:181], v[190:191], off offset:1024
	global_load_dwordx4 v[182:185], v[190:191], off offset:2048
	global_load_dwordx4 v[186:189], v[190:191], off offset:3072
	s_waitcnt vmcnt(7)
	v_add_f32_e32 v96, v158, v159
	v_add_f32_e32 v98, v160, v161
	v_add_f32_e32 v96, v96, v98
	v_mov_b32_e32 v98, v96
	s_nop 1
	v_permlane16_swap_b32_e32 v96, v98
	v_add_f32_e32 v96, v96, v98
	v_mov_b32_e32 v98, v96
	s_nop 1
	v_permlane32_swap_b32_e32 v96, v98
	v_add_f32_e32 v96, v96, v98
	v_fmamk_f32 v96, v96, 0x3a800000, v225
	v_mul_f32_e32 v98, 0x4b800000, v96
	v_cmp_gt_f32_e32 vcc, s3, v96
	s_nop 1
	v_cndmask_b32_e32 v96, v96, v98, vcc
	v_rsq_f32_e32 v96, v96
	s_nop 0
	v_mul_f32_e32 v98, 0x45800000, v96
	v_cndmask_b32_e32 v96, v96, v98, vcc

.LBB0_440:
	v_add_u32_e32 v98, s8, v247
	v_ashrrev_i32_e32 v99, 31, v98
	v_lshl_add_u64 v[134:135], v[98:99], 1, s[30:31]
	v_mad_u64_u32 v[152:153], s[30:31], v132, s93, 0
	v_mov_b32_e32 v96, v153
	v_mad_u64_u32 v[154:155], s[30:31], v133, s93, v[96:97]
	v_mov_b32_e32 v153, v154
	v_lshl_add_u64 v[152:153], v[152:153], 1, v[134:135]
	v_cvt_pk_bf16_f32 v148, v148, v149
	v_cvt_pk_bf16_f32 v149, v150, v151
	v_cvt_pk_bf16_f32 v151, v136, v137
	v_cvt_pk_bf16_f32 v136, v138, v139
	v_cvt_pk_bf16_f32 v137, v142, v143
	v_cvt_pk_bf16_f32 v138, v146, v147
	v_cvt_pk_bf16_f32 v139, v144, v145
	global_store_dwordx4 v[152:153], v[136:139], off offset:256
	v_cndmask_b32_e64 v96, 0, 1, s[88:89]
	v_cvt_pk_bf16_f32 v150, v140, v141
	v_or_b32_e32 v136, 16, v132
	v_cmp_ne_u32_e64 s[44:45], 1, v96
	s_andn2_b64 vcc, exec, s[88:89]
	v_ashrrev_i32_e32 v137, 31, v136
	global_store_dwordx4 v[152:153], v[148:151], off
	s_cbranch_vccnz .LBB0_442
	v_lshlrev_b64 v[138:139], 6, v[136:137]
	v_lshl_add_u64 v[138:139], v[206:207], 0, v[138:139]
	s_waitcnt vmcnt(7)
	v_add_f32_e32 v96, v162, v163
	v_add_f32_e32 v133, v164, v165
	v_add_f32_e32 v96, v96, v133
	v_mov_b32_e32 v133, v96
	s_nop 1
	v_permlane16_swap_b32_e32 v96, v133
	v_add_f32_e32 v96, v96, v133
	v_mov_b32_e32 v133, v96
	s_nop 1
	v_permlane32_swap_b32_e32 v96, v133
	v_add_f32_e32 v96, v96, v133
	v_fmamk_f32 v96, v96, 0x3a800000, v225
	v_mul_f32_e32 v133, 0x4b800000, v96
	v_cmp_gt_f32_e32 vcc, s3, v96
	s_nop 1
	v_cndmask_b32_e32 v96, v96, v133, vcc
	v_rsq_f32_e32 v96, v96
	s_nop 0
	v_mul_f32_e32 v133, 0x45800000, v96
	v_cndmask_b32_e32 v96, v96, v133, vcc
	s_branch .LBB0_443

.LBB0_447:
	v_mad_u64_u32 v[138:139], s[30:31], v136, s93, 0
	v_mov_b32_e32 v96, v139
	v_mad_u64_u32 v[136:137], s[30:31], v137, s93, v[96:97]
	v_mov_b32_e32 v139, v136
	v_cvt_pk_bf16_f32 v120, v120, v121
	v_cvt_pk_bf16_f32 v121, v122, v123
	v_cvt_pk_bf16_f32 v122, v116, v117
	v_or_b32_e32 v116, 32, v132
	v_lshl_add_u64 v[136:137], v[138:139], 1, v[134:135]
	v_cvt_pk_bf16_f32 v128, v128, v129
	v_cvt_pk_bf16_f32 v129, v130, v131
	v_cvt_pk_bf16_f32 v130, v124, v125
	v_cvt_pk_bf16_f32 v131, v126, v127
	v_cvt_pk_bf16_f32 v123, v118, v119
	s_and_b64 vcc, exec, s[44:45]
	v_ashrrev_i32_e32 v117, 31, v116
	global_store_dwordx4 v[136:137], v[128:131], off
	global_store_dwordx4 v[136:137], v[120:123], off offset:256
	s_cbranch_vccnz .LBB0_449
	v_lshlrev_b64 v[118:119], 6, v[116:117]
	v_lshl_add_u64 v[118:119], v[206:207], 0, v[118:119]
	s_waitcnt vmcnt(7)
	v_add_f32_e32 v96, v166, v167
	v_add_f32_e32 v118, v168, v169
	v_add_f32_e32 v96, v96, v118
	v_mov_b32_e32 v118, v96
	s_nop 1
	v_permlane16_swap_b32_e32 v96, v118
	v_add_f32_e32 v96, v96, v118
	v_mov_b32_e32 v118, v96
	s_nop 1
	v_permlane32_swap_b32_e32 v96, v118
	v_add_f32_e32 v96, v96, v118
	v_fmamk_f32 v96, v96, 0x3a800000, v225
	v_mul_f32_e32 v118, 0x4b800000, v96
	v_cmp_gt_f32_e32 vcc, s3, v96
	s_nop 1
	v_cndmask_b32_e32 v96, v96, v118, vcc
	v_rsq_f32_e32 v96, v96
	s_nop 0
	v_mul_f32_e32 v118, 0x45800000, v96
	v_cndmask_b32_e32 v96, v96, v118, vcc
	s_branch .LBB0_450

.LBB0_454:
	v_mad_u64_u32 v[118:119], s[30:31], v116, s93, 0
	v_mov_b32_e32 v96, v119
	v_mad_u64_u32 v[116:117], s[30:31], v117, s93, v[96:97]
	v_mov_b32_e32 v119, v116
	v_cvt_pk_bf16_f32 v104, v104, v105
	v_cvt_pk_bf16_f32 v105, v106, v107
	v_cvt_pk_bf16_f32 v106, v100, v101
	v_or_b32_e32 v100, 48, v132
	v_lshl_add_u64 v[116:117], v[118:119], 1, v[134:135]
	v_cvt_pk_bf16_f32 v112, v112, v113
	v_cvt_pk_bf16_f32 v113, v114, v115
	v_cvt_pk_bf16_f32 v114, v108, v109
	v_cvt_pk_bf16_f32 v115, v110, v111
	v_cvt_pk_bf16_f32 v107, v102, v103
	s_and_b64 vcc, exec, s[44:45]
	v_ashrrev_i32_e32 v101, 31, v100
	global_store_dwordx4 v[116:117], v[112:115], off
	global_store_dwordx4 v[116:117], v[104:107], off offset:256
	s_cbranch_vccnz .LBB0_456
	v_lshlrev_b64 v[102:103], 6, v[100:101]
	v_lshl_add_u64 v[102:103], v[206:207], 0, v[102:103]
	s_waitcnt vmcnt(7)
	v_add_f32_e32 v96, v170, v171
	v_add_f32_e32 v102, v172, v173
	v_add_f32_e32 v96, v96, v102
	v_mov_b32_e32 v102, v96
	s_nop 1
	v_permlane16_swap_b32_e32 v96, v102
	v_add_f32_e32 v96, v96, v102
	v_mov_b32_e32 v102, v96
	s_nop 1
	v_permlane32_swap_b32_e32 v96, v102
	v_add_f32_e32 v96, v96, v102
	v_fmamk_f32 v96, v96, 0x3a800000, v225
	v_mul_f32_e32 v102, 0x4b800000, v96
	v_cmp_gt_f32_e32 vcc, s3, v96
	s_nop 1
	v_cndmask_b32_e32 v96, v96, v102, vcc
	v_rsq_f32_e32 v96, v96
	s_nop 0
	v_mul_f32_e32 v102, 0x45800000, v96
	v_cndmask_b32_e32 v96, v96, v102, vcc
	s_branch .LBB0_457

.LBB0_461:
	v_mad_u64_u32 v[102:103], s[30:31], v100, s93, 0
	v_mov_b32_e32 v96, v103
	v_mad_u64_u32 v[100:101], s[30:31], v101, s93, v[96:97]
	v_mov_b32_e32 v103, v100
	v_cvt_pk_bf16_f32 v84, v84, v85
	v_cvt_pk_bf16_f32 v85, v86, v87
	v_cvt_pk_bf16_f32 v86, v80, v81
	v_add_u32_e32 v80, 0x80, v132
	v_lshl_add_u64 v[100:101], v[102:103], 1, v[134:135]
	v_cvt_pk_bf16_f32 v92, v92, v93
	v_cvt_pk_bf16_f32 v93, v94, v95
	v_cvt_pk_bf16_f32 v94, v88, v89
	v_cvt_pk_bf16_f32 v95, v90, v91
	v_cvt_pk_bf16_f32 v87, v82, v83
	s_and_b64 vcc, exec, s[44:45]
	v_ashrrev_i32_e32 v81, 31, v80
	global_store_dwordx4 v[100:101], v[92:95], off
	global_store_dwordx4 v[100:101], v[84:87], off offset:256
	s_cbranch_vccnz .LBB0_463
	v_lshlrev_b64 v[82:83], 6, v[80:81]
	v_lshl_add_u64 v[82:83], v[206:207], 0, v[82:83]
	s_waitcnt vmcnt(7)
	v_add_f32_e32 v82, v174, v175
	v_add_f32_e32 v83, v176, v177
	v_add_f32_e32 v82, v82, v83
	v_mov_b32_e32 v83, v82
	s_nop 1
	v_permlane16_swap_b32_e32 v82, v83
	v_add_f32_e32 v82, v82, v83
	v_mov_b32_e32 v83, v82
	s_nop 1
	v_permlane32_swap_b32_e32 v82, v83
	v_add_f32_e32 v82, v82, v83
	v_fmamk_f32 v82, v82, 0x3a800000, v225
	v_mul_f32_e32 v83, 0x4b800000, v82
	v_cmp_gt_f32_e32 vcc, s3, v82
	s_nop 1
	v_cndmask_b32_e32 v82, v82, v83, vcc
	v_rsq_f32_e32 v82, v82
	s_nop 0
	v_mul_f32_e32 v83, 0x45800000, v82
	v_cndmask_b32_e32 v86, v82, v83, vcc
	s_branch .LBB0_464

.LBB0_468:
	v_mad_u64_u32 v[72:73], s[30:31], v80, s93, 0
	v_mov_b32_e32 v78, v73
	v_mad_u64_u32 v[78:79], s[30:31], v81, s93, v[78:79]
	v_mov_b32_e32 v73, v78
	v_lshl_add_u64 v[72:73], v[72:73], 1, v[134:135]
	v_cvt_pk_bf16_f32 v81, v64, v65
	v_cvt_pk_bf16_f32 v64, v66, v67
	v_cvt_pk_bf16_f32 v65, v74, v75
	v_cvt_pk_bf16_f32 v66, v68, v69
	v_cvt_pk_bf16_f32 v67, v70, v71
	global_store_dwordx4 v[72:73], v[64:67], off offset:256
	v_cvt_pk_bf16_f32 v78, v82, v83
	v_cvt_pk_bf16_f32 v79, v84, v85
	v_add_u32_e32 v64, 0x90, v132
	v_cvt_pk_bf16_f32 v80, v76, v77
	s_and_b64 vcc, exec, s[44:45]
	v_ashrrev_i32_e32 v65, 31, v64
	global_store_dwordx4 v[72:73], v[78:81], off
	s_cbranch_vccnz .LBB0_470
	v_lshlrev_b64 v[66:67], 6, v[64:65]
	v_lshl_add_u64 v[66:67], v[206:207], 0, v[66:67]
	s_waitcnt vmcnt(7)
	v_add_f32_e32 v66, v178, v179
	v_add_f32_e32 v67, v180, v181
	v_add_f32_e32 v66, v66, v67
	v_mov_b32_e32 v67, v66
	s_nop 1
	v_permlane16_swap_b32_e32 v66, v67
	v_add_f32_e32 v66, v66, v67
	v_mov_b32_e32 v67, v66
	s_nop 1
	v_permlane32_swap_b32_e32 v66, v67
	v_add_f32_e32 v66, v66, v67
	v_fmamk_f32 v66, v66, 0x3a800000, v225
	v_mul_f32_e32 v67, 0x4b800000, v66
	v_cmp_gt_f32_e32 vcc, s3, v66
	s_nop 1
	v_cndmask_b32_e32 v66, v66, v67, vcc
	v_rsq_f32_e32 v66, v66
	s_nop 0
	v_mul_f32_e32 v67, 0x45800000, v66
	v_cndmask_b32_e32 v66, v66, v67, vcc
	s_branch .LBB0_471

.LBB0_475:
	v_mad_u64_u32 v[66:67], s[30:31], v64, s93, 0
	v_mov_b32_e32 v64, v67
	v_mad_u64_u32 v[64:65], s[30:31], v65, s93, v[64:65]
	v_mov_b32_e32 v67, v64
	v_cvt_pk_bf16_f32 v44, v44, v45
	v_cvt_pk_bf16_f32 v45, v46, v47
	v_cvt_pk_bf16_f32 v46, v40, v41
	v_add_u32_e32 v40, 0xa0, v132
	v_lshl_add_u64 v[64:65], v[66:67], 1, v[134:135]
	v_cvt_pk_bf16_f32 v56, v56, v57
	v_cvt_pk_bf16_f32 v57, v58, v59
	v_cvt_pk_bf16_f32 v58, v52, v53
	v_cvt_pk_bf16_f32 v59, v54, v55
	v_cvt_pk_bf16_f32 v47, v42, v43
	s_and_b64 vcc, exec, s[44:45]
	v_ashrrev_i32_e32 v41, 31, v40
	global_store_dwordx4 v[64:65], v[56:59], off
	global_store_dwordx4 v[64:65], v[44:47], off offset:256
	s_cbranch_vccnz .LBB0_477
	v_lshlrev_b64 v[42:43], 6, v[40:41]
	v_lshl_add_u64 v[42:43], v[206:207], 0, v[42:43]
	s_waitcnt vmcnt(7)
	v_add_f32_e32 v42, v182, v183
	v_add_f32_e32 v43, v184, v185
	v_add_f32_e32 v42, v42, v43
	v_mov_b32_e32 v43, v42
	s_nop 1
	v_permlane16_swap_b32_e32 v42, v43
	v_add_f32_e32 v42, v42, v43
	v_mov_b32_e32 v43, v42
	s_nop 1
	v_permlane32_swap_b32_e32 v42, v43
	v_add_f32_e32 v42, v42, v43
	v_fmamk_f32 v42, v42, 0x3a800000, v225
	v_mul_f32_e32 v43, 0x4b800000, v42
	v_cmp_gt_f32_e32 vcc, s3, v42
	s_nop 1
	v_cndmask_b32_e32 v42, v42, v43, vcc
	v_rsq_f32_e32 v42, v42
	s_nop 0
	v_mul_f32_e32 v43, 0x45800000, v42
	v_cndmask_b32_e32 v42, v42, v43, vcc
	s_branch .LBB0_478

.LBB0_482:
	v_mad_u64_u32 v[42:43], s[30:31], v40, s93, 0
	v_mov_b32_e32 v40, v43
	v_mad_u64_u32 v[40:41], s[30:31], v41, s93, v[40:41]
	v_mov_b32_e32 v43, v40
	v_cvt_pk_bf16_f32 v20, v20, v21
	v_cvt_pk_bf16_f32 v21, v22, v23
	v_cvt_pk_bf16_f32 v22, v16, v17
	v_add_u32_e32 v16, 0xb0, v132
	v_lshl_add_u64 v[40:41], v[42:43], 1, v[134:135]
	v_cvt_pk_bf16_f32 v28, v28, v29
	v_cvt_pk_bf16_f32 v29, v30, v31
	v_cvt_pk_bf16_f32 v30, v24, v25
	v_cvt_pk_bf16_f32 v31, v26, v27
	v_cvt_pk_bf16_f32 v23, v18, v19
	s_and_b64 vcc, exec, s[44:45]
	v_ashrrev_i32_e32 v17, 31, v16
	global_store_dwordx4 v[40:41], v[28:31], off
	global_store_dwordx4 v[40:41], v[20:23], off offset:256
	s_cbranch_vccnz .LBB0_484
	v_lshlrev_b64 v[18:19], 6, v[16:17]
	v_lshl_add_u64 v[18:19], v[206:207], 0, v[18:19]
	s_waitcnt vmcnt(7)
	v_add_f32_e32 v18, v186, v187
	v_add_f32_e32 v19, v188, v189
	v_add_f32_e32 v18, v18, v19
	v_mov_b32_e32 v19, v18
	s_nop 1
	v_permlane16_swap_b32_e32 v18, v19
	v_add_f32_e32 v18, v18, v19
	v_mov_b32_e32 v19, v18
	s_nop 1
	v_permlane32_swap_b32_e32 v18, v19
	v_add_f32_e32 v18, v18, v19
	v_fmamk_f32 v18, v18, 0x3a800000, v225
	v_mul_f32_e32 v19, 0x4b800000, v18
	v_cmp_gt_f32_e32 vcc, s3, v18
	s_nop 1
	v_cndmask_b32_e32 v18, v18, v19, vcc
	v_rsq_f32_e32 v18, v18
	s_nop 0
	v_mul_f32_e32 v19, 0x45800000, v18
	v_cndmask_b32_e32 v18, v18, v19, vcc
	s_branch .LBB0_485

.LBB0_542:
	v_lshl_add_u32 v130, s68, 8, v205
	v_ashrrev_i32_e32 v131, 31, v130
	v_lshlrev_b64 v[132:133], 6, v[130:131]
	v_lshl_add_u64 v[132:133], v[206:207], 0, v[132:133]
	global_load_dwordx4 v[146:149], v[132:133], off
	global_load_dwordx4 v[150:153], v[132:133], off offset:1024
	global_load_dwordx4 v[154:157], v[132:133], off offset:2048
	global_load_dwordx4 v[158:161], v[132:133], off offset:3072
	v_add_u32_e32 v178, 0x80, v130
	v_ashrrev_i32_e32 v179, 31, v178
	v_lshlrev_b64 v[178:179], 6, v[178:179]
	v_lshl_add_u64 v[178:179], v[206:207], 0, v[178:179]
	global_load_dwordx4 v[162:165], v[178:179], off
	global_load_dwordx4 v[166:169], v[178:179], off offset:1024
	global_load_dwordx4 v[170:173], v[178:179], off offset:2048
	global_load_dwordx4 v[174:177], v[178:179], off offset:3072
	s_cmp_gt_i32 s77, 7
	s_cselect_b64 s[40:41], -1, 0
	s_lshl_b32 s30, s77, 8
	s_add_i32 s68, s30, 0xfffff800
	s_mov_b64 s[38:39], -1
	s_waitcnt vmcnt(7)
	v_add_f32_e32 v96, v146, v147
	v_add_f32_e32 v132, v148, v149
	v_add_f32_e32 v96, v96, v132
	v_mov_b32_e32 v132, v96
	s_nop 1
	v_permlane16_swap_b32_e32 v96, v132
	v_add_f32_e32 v96, v96, v132
	v_mov_b32_e32 v132, v96
	s_nop 1
	v_permlane32_swap_b32_e32 v96, v132
	v_add_f32_e32 v96, v96, v132
	v_fmamk_f32 v96, v96, 0x3a800000, v225
	v_cmp_gt_f32_e32 vcc, s3, v96
	v_mul_f32_e32 v132, 0x4b800000, v96
	v_lshlrev_b64 v[134:135], 11, v[130:131]
	v_cndmask_b32_e32 v96, v96, v132, vcc
	v_rsq_f32_e32 v96, v96
	s_nop 0
	v_mul_f32_e32 v132, 0x45800000, v96
	v_cndmask_b32_e32 v132, v96, v132, vcc
	s_and_b64 vcc, exec, s[40:41]
	v_lshlrev_b32_e32 v96, 1, v204
	s_cbranch_vccz .LBB0_544
	v_lshl_add_u64 v[136:137], s[26:27], 0, v[134:135]
	v_lshl_add_u64 v[136:137], s[68:69], 1, v[136:137]
	s_lshl_b32 s30, s62, 1
	s_mov_b32 s31, s69
	v_lshl_add_u64 v[136:137], v[136:137], 0, s[30:31]
	v_lshl_add_u64 v[140:141], v[136:137], 0, v[96:97]
	v_pk_mul_f32 v[138:139], v[128:129], v[132:133] op_sel_hi:[1,0]
	v_pk_mul_f32 v[136:137], v[126:127], v[132:133] op_sel_hi:[1,0]
	v_pk_mul_f32 v[142:143], v[120:121], v[132:133] op_sel_hi:[1,0]
	v_pk_mul_f32 v[144:145], v[118:119], v[132:133] op_sel_hi:[1,0]
	v_cvt_pk_bf16_f32 v136, v136, v137
	v_cvt_pk_bf16_f32 v137, v138, v139
	v_cvt_pk_bf16_f32 v138, v144, v145
	v_cvt_pk_bf16_f32 v139, v142, v143
	global_store_dwordx4 v[140:141], v[136:139], off nt
	v_pk_mul_f32 v[142:143], v[116:117], v[132:133] op_sel_hi:[1,0]
	v_pk_mul_f32 v[144:145], v[114:115], v[132:133] op_sel_hi:[1,0]
	v_pk_mul_f32 v[138:139], v[124:125], v[132:133] op_sel_hi:[1,0]
	v_pk_mul_f32 v[136:137], v[122:123], v[132:133] op_sel_hi:[1,0]
	s_mov_b64 s[38:39], 0
	v_cvt_pk_bf16_f32 v136, v136, v137
	v_cvt_pk_bf16_f32 v137, v138, v139
	v_cvt_pk_bf16_f32 v138, v144, v145
	v_cvt_pk_bf16_f32 v139, v142, v143
	global_store_dwordx4 v[140:141], v[136:139], off offset:256 nt

.LBB0_546:
	v_or_b32_e32 v118, 16, v130
	v_ashrrev_i32_e32 v119, 31, v118
	v_lshlrev_b64 v[114:115], 6, v[118:119]
	v_lshl_add_u64 v[114:115], v[206:207], 0, v[114:115]
	s_mov_b64 s[60:61], -1
	s_waitcnt vmcnt(7)
	v_add_f32_e32 v114, v150, v151
	v_add_f32_e32 v115, v152, v153
	v_add_f32_e32 v114, v114, v115
	v_mov_b32_e32 v115, v114
	s_nop 1
	v_permlane16_swap_b32_e32 v114, v115
	v_add_f32_e32 v114, v114, v115
	v_mov_b32_e32 v115, v114
	s_nop 1
	v_permlane32_swap_b32_e32 v114, v115
	v_add_f32_e32 v114, v114, v115
	v_fmamk_f32 v114, v114, 0x3a800000, v225
	v_cmp_gt_f32_e32 vcc, s3, v114
	v_mul_f32_e32 v115, 0x4b800000, v114
	v_lshlrev_b64 v[116:117], 11, v[118:119]
	v_cndmask_b32_e32 v114, v114, v115, vcc
	v_rsq_f32_e32 v114, v114
	s_nop 0
	v_mul_f32_e32 v115, 0x45800000, v114
	v_cndmask_b32_e32 v114, v114, v115, vcc
	v_cndmask_b32_e64 v115, 0, 1, s[40:41]
	v_cmp_ne_u32_e64 s[38:39], 1, v115
	s_andn2_b64 vcc, exec, s[40:41]
	s_cbranch_vccnz .LBB0_548
	v_lshl_add_u64 v[118:119], s[26:27], 0, v[116:117]
	v_lshl_add_u64 v[118:119], s[68:69], 1, v[118:119]
	s_lshl_b32 s40, s62, 1
	s_mov_b32 s41, s69
	v_lshl_add_u64 v[118:119], v[118:119], 0, s[40:41]
	v_lshl_add_u64 v[122:123], v[118:119], 0, v[96:97]
	v_pk_mul_f32 v[120:121], v[112:113], v[114:115] op_sel_hi:[1,0]
	v_pk_mul_f32 v[118:119], v[110:111], v[114:115] op_sel_hi:[1,0]
	v_pk_mul_f32 v[124:125], v[104:105], v[114:115] op_sel_hi:[1,0]
	v_pk_mul_f32 v[126:127], v[102:103], v[114:115] op_sel_hi:[1,0]
	v_cvt_pk_bf16_f32 v118, v118, v119
	v_cvt_pk_bf16_f32 v119, v120, v121
	v_cvt_pk_bf16_f32 v120, v126, v127
	v_cvt_pk_bf16_f32 v121, v124, v125
	global_store_dwordx4 v[122:123], v[118:121], off nt
	v_pk_mul_f32 v[124:125], v[100:101], v[114:115] op_sel_hi:[1,0]
	v_pk_mul_f32 v[126:127], v[98:99], v[114:115] op_sel_hi:[1,0]
	v_pk_mul_f32 v[120:121], v[108:109], v[114:115] op_sel_hi:[1,0]
	v_pk_mul_f32 v[118:119], v[106:107], v[114:115] op_sel_hi:[1,0]
	s_mov_b64 s[60:61], 0
	v_cvt_pk_bf16_f32 v118, v118, v119
	v_cvt_pk_bf16_f32 v119, v120, v121
	v_cvt_pk_bf16_f32 v120, v126, v127
	v_cvt_pk_bf16_f32 v121, v124, v125
	global_store_dwordx4 v[122:123], v[118:121], off offset:256 nt

.LBB0_550:
	v_or_b32_e32 v102, 32, v130
	v_ashrrev_i32_e32 v103, 31, v102
	v_lshlrev_b64 v[98:99], 6, v[102:103]
	v_lshl_add_u64 v[98:99], v[206:207], 0, v[98:99]
	s_mov_b64 s[40:41], -1
	s_waitcnt vmcnt(7)
	v_add_f32_e32 v98, v154, v155
	v_add_f32_e32 v99, v156, v157
	v_add_f32_e32 v98, v98, v99
	v_mov_b32_e32 v99, v98
	s_nop 1
	v_permlane16_swap_b32_e32 v98, v99
	v_add_f32_e32 v98, v98, v99
	v_mov_b32_e32 v99, v98
	s_nop 1
	v_permlane32_swap_b32_e32 v98, v99
	v_add_f32_e32 v98, v98, v99
	v_fmamk_f32 v98, v98, 0x3a800000, v225
	v_cmp_gt_f32_e32 vcc, s3, v98
	v_mul_f32_e32 v99, 0x4b800000, v98
	s_nop 0
	v_cndmask_b32_e32 v98, v98, v99, vcc
	v_rsq_f32_e32 v98, v98
	s_nop 0
	v_mul_f32_e32 v99, 0x45800000, v98
	v_cndmask_b32_e32 v100, v98, v99, vcc
	s_and_b64 vcc, exec, s[38:39]
	v_lshlrev_b64 v[98:99], 11, v[102:103]
	s_cbranch_vccnz .LBB0_552
	v_lshl_add_u64 v[102:103], s[26:27], 0, v[98:99]
	v_lshl_add_u64 v[102:103], s[68:69], 1, v[102:103]
	s_lshl_b32 s40, s62, 1
	s_mov_b32 s41, s69
	v_lshl_add_u64 v[102:103], v[102:103], 0, s[40:41]
	v_lshl_add_u64 v[106:107], v[102:103], 0, v[96:97]
	v_pk_mul_f32 v[104:105], v[94:95], v[100:101] op_sel_hi:[1,0]
	v_pk_mul_f32 v[102:103], v[92:93], v[100:101] op_sel_hi:[1,0]
	v_pk_mul_f32 v[108:109], v[86:87], v[100:101] op_sel_hi:[1,0]
	v_pk_mul_f32 v[110:111], v[84:85], v[100:101] op_sel_hi:[1,0]
	v_cvt_pk_bf16_f32 v102, v102, v103
	v_cvt_pk_bf16_f32 v103, v104, v105
	v_cvt_pk_bf16_f32 v104, v110, v111
	v_cvt_pk_bf16_f32 v105, v108, v109
	global_store_dwordx4 v[106:107], v[102:105], off nt
	v_pk_mul_f32 v[108:109], v[82:83], v[100:101] op_sel_hi:[1,0]
	v_pk_mul_f32 v[110:111], v[80:81], v[100:101] op_sel_hi:[1,0]
	v_pk_mul_f32 v[104:105], v[90:91], v[100:101] op_sel_hi:[1,0]
	v_pk_mul_f32 v[102:103], v[88:89], v[100:101] op_sel_hi:[1,0]
	s_mov_b64 s[40:41], 0
	v_cvt_pk_bf16_f32 v102, v102, v103
	v_cvt_pk_bf16_f32 v103, v104, v105
	v_cvt_pk_bf16_f32 v104, v110, v111
	v_cvt_pk_bf16_f32 v105, v108, v109
	global_store_dwordx4 v[106:107], v[102:105], off offset:256 nt

.LBB0_554:
	v_or_b32_e32 v84, 48, v130
	v_ashrrev_i32_e32 v85, 31, v84
	v_lshlrev_b64 v[80:81], 6, v[84:85]
	v_lshl_add_u64 v[80:81], v[206:207], 0, v[80:81]
	s_mov_b64 s[40:41], -1
	s_waitcnt vmcnt(7)
	v_add_f32_e32 v80, v158, v159
	v_add_f32_e32 v81, v160, v161
	v_add_f32_e32 v80, v80, v81
	v_mov_b32_e32 v81, v80
	s_nop 1
	v_permlane16_swap_b32_e32 v80, v81
	v_add_f32_e32 v80, v80, v81
	v_mov_b32_e32 v81, v80
	s_nop 1
	v_permlane32_swap_b32_e32 v80, v81
	v_add_f32_e32 v80, v80, v81
	v_fmamk_f32 v80, v80, 0x3a800000, v225
	v_cmp_gt_f32_e32 vcc, s3, v80
	v_mul_f32_e32 v81, 0x4b800000, v80
	s_nop 0
	v_cndmask_b32_e32 v80, v80, v81, vcc
	v_rsq_f32_e32 v80, v80
	s_nop 0
	v_mul_f32_e32 v81, 0x45800000, v80
	v_cndmask_b32_e32 v82, v80, v81, vcc
	s_and_b64 vcc, exec, s[38:39]
	v_lshlrev_b64 v[80:81], 11, v[84:85]
	s_cbranch_vccnz .LBB0_556
	v_lshl_add_u64 v[84:85], s[26:27], 0, v[80:81]
	v_lshl_add_u64 v[84:85], s[68:69], 1, v[84:85]
	s_lshl_b32 s40, s62, 1
	s_mov_b32 s41, s69
	v_lshl_add_u64 v[84:85], v[84:85], 0, s[40:41]
	v_lshl_add_u64 v[88:89], v[84:85], 0, v[96:97]
	v_pk_mul_f32 v[86:87], v[78:79], v[82:83] op_sel_hi:[1,0]
	v_pk_mul_f32 v[84:85], v[76:77], v[82:83] op_sel_hi:[1,0]
	v_pk_mul_f32 v[90:91], v[70:71], v[82:83] op_sel_hi:[1,0]
	v_pk_mul_f32 v[92:93], v[68:69], v[82:83] op_sel_hi:[1,0]
	v_cvt_pk_bf16_f32 v84, v84, v85
	v_cvt_pk_bf16_f32 v85, v86, v87
	v_cvt_pk_bf16_f32 v86, v92, v93
	v_cvt_pk_bf16_f32 v87, v90, v91
	global_store_dwordx4 v[88:89], v[84:87], off nt
	v_pk_mul_f32 v[90:91], v[66:67], v[82:83] op_sel_hi:[1,0]
	v_pk_mul_f32 v[92:93], v[64:65], v[82:83] op_sel_hi:[1,0]
	v_pk_mul_f32 v[86:87], v[74:75], v[82:83] op_sel_hi:[1,0]
	v_pk_mul_f32 v[84:85], v[72:73], v[82:83] op_sel_hi:[1,0]
	s_mov_b64 s[40:41], 0
	v_cvt_pk_bf16_f32 v84, v84, v85
	v_cvt_pk_bf16_f32 v85, v86, v87
	v_cvt_pk_bf16_f32 v86, v92, v93
	v_cvt_pk_bf16_f32 v87, v90, v91
	global_store_dwordx4 v[88:89], v[84:87], off offset:256 nt

.LBB0_558:
	v_add_u32_e32 v68, 0x80, v130
	v_ashrrev_i32_e32 v69, 31, v68
	v_lshlrev_b64 v[64:65], 6, v[68:69]
	v_lshl_add_u64 v[64:65], v[206:207], 0, v[64:65]
	s_mov_b64 s[40:41], -1
	s_waitcnt vmcnt(7)
	v_add_f32_e32 v64, v162, v163
	v_add_f32_e32 v65, v164, v165
	v_add_f32_e32 v64, v64, v65
	v_mov_b32_e32 v65, v64
	s_nop 1
	v_permlane16_swap_b32_e32 v64, v65
	v_add_f32_e32 v64, v64, v65
	v_mov_b32_e32 v65, v64
	s_nop 1
	v_permlane32_swap_b32_e32 v64, v65
	v_add_f32_e32 v64, v64, v65
	v_fmamk_f32 v64, v64, 0x3a800000, v225
	v_cmp_gt_f32_e32 vcc, s3, v64
	v_mul_f32_e32 v65, 0x4b800000, v64
	s_nop 0
	v_cndmask_b32_e32 v64, v64, v65, vcc
	v_rsq_f32_e32 v64, v64
	s_nop 0
	v_mul_f32_e32 v65, 0x45800000, v64
	v_cndmask_b32_e32 v66, v64, v65, vcc
	s_and_b64 vcc, exec, s[38:39]
	v_lshlrev_b64 v[64:65], 11, v[68:69]
	s_cbranch_vccnz .LBB0_560
	v_lshl_add_u64 v[68:69], s[26:27], 0, v[64:65]
	v_lshl_add_u64 v[68:69], s[68:69], 1, v[68:69]
	s_lshl_b32 s40, s62, 1
	s_mov_b32 s41, s69
	v_lshl_add_u64 v[68:69], v[68:69], 0, s[40:41]
	v_lshl_add_u64 v[72:73], v[68:69], 0, v[96:97]
	v_pk_mul_f32 v[70:71], v[50:51], v[66:67] op_sel_hi:[1,0]
	v_pk_mul_f32 v[68:69], v[48:49], v[66:67] op_sel_hi:[1,0]
	v_pk_mul_f32 v[74:75], v[58:59], v[66:67] op_sel_hi:[1,0]
	v_pk_mul_f32 v[76:77], v[56:57], v[66:67] op_sel_hi:[1,0]
	v_cvt_pk_bf16_f32 v68, v68, v69
	v_cvt_pk_bf16_f32 v69, v70, v71
	v_cvt_pk_bf16_f32 v70, v76, v77
	v_cvt_pk_bf16_f32 v71, v74, v75
	global_store_dwordx4 v[72:73], v[68:71], off nt
	v_pk_mul_f32 v[74:75], v[54:55], v[66:67] op_sel_hi:[1,0]
	v_pk_mul_f32 v[76:77], v[52:53], v[66:67] op_sel_hi:[1,0]
	v_pk_mul_f32 v[70:71], v[62:63], v[66:67] op_sel_hi:[1,0]
	v_pk_mul_f32 v[68:69], v[60:61], v[66:67] op_sel_hi:[1,0]
	s_mov_b64 s[40:41], 0
	v_cvt_pk_bf16_f32 v68, v68, v69
	v_cvt_pk_bf16_f32 v69, v70, v71
	v_cvt_pk_bf16_f32 v70, v76, v77
	v_cvt_pk_bf16_f32 v71, v74, v75
	global_store_dwordx4 v[72:73], v[68:71], off offset:256 nt

.LBB0_562:
	v_add_u32_e32 v52, 0x90, v130
	v_ashrrev_i32_e32 v53, 31, v52
	v_lshlrev_b64 v[48:49], 6, v[52:53]
	v_lshl_add_u64 v[48:49], v[206:207], 0, v[48:49]
	s_mov_b64 s[40:41], -1
	s_waitcnt vmcnt(7)
	v_add_f32_e32 v48, v166, v167
	v_add_f32_e32 v49, v168, v169
	v_add_f32_e32 v48, v48, v49
	v_mov_b32_e32 v49, v48
	s_nop 1
	v_permlane16_swap_b32_e32 v48, v49
	v_add_f32_e32 v48, v48, v49
	v_mov_b32_e32 v49, v48
	s_nop 1
	v_permlane32_swap_b32_e32 v48, v49
	v_add_f32_e32 v48, v48, v49
	v_fmamk_f32 v48, v48, 0x3a800000, v225
	v_cmp_gt_f32_e32 vcc, s3, v48
	v_mul_f32_e32 v49, 0x4b800000, v48
	s_nop 0
	v_cndmask_b32_e32 v48, v48, v49, vcc
	v_rsq_f32_e32 v48, v48
	s_nop 0
	v_mul_f32_e32 v49, 0x45800000, v48
	v_cndmask_b32_e32 v50, v48, v49, vcc
	s_and_b64 vcc, exec, s[38:39]
	v_lshlrev_b64 v[48:49], 11, v[52:53]
	s_cbranch_vccnz .LBB0_564
	v_lshl_add_u64 v[52:53], s[26:27], 0, v[48:49]
	v_lshl_add_u64 v[52:53], s[68:69], 1, v[52:53]
	s_lshl_b32 s40, s62, 1
	s_mov_b32 s41, s69
	v_lshl_add_u64 v[52:53], v[52:53], 0, s[40:41]
	v_lshl_add_u64 v[56:57], v[52:53], 0, v[96:97]
	v_pk_mul_f32 v[54:55], v[46:47], v[50:51] op_sel_hi:[1,0]
	v_pk_mul_f32 v[52:53], v[44:45], v[50:51] op_sel_hi:[1,0]
	v_pk_mul_f32 v[58:59], v[38:39], v[50:51] op_sel_hi:[1,0]
	v_pk_mul_f32 v[60:61], v[36:37], v[50:51] op_sel_hi:[1,0]
	v_cvt_pk_bf16_f32 v52, v52, v53
	v_cvt_pk_bf16_f32 v53, v54, v55
	v_cvt_pk_bf16_f32 v54, v60, v61
	v_cvt_pk_bf16_f32 v55, v58, v59
	global_store_dwordx4 v[56:57], v[52:55], off nt
	v_pk_mul_f32 v[58:59], v[34:35], v[50:51] op_sel_hi:[1,0]
	v_pk_mul_f32 v[60:61], v[32:33], v[50:51] op_sel_hi:[1,0]
	v_pk_mul_f32 v[54:55], v[42:43], v[50:51] op_sel_hi:[1,0]
	v_pk_mul_f32 v[52:53], v[40:41], v[50:51] op_sel_hi:[1,0]
	s_mov_b64 s[40:41], 0
	v_cvt_pk_bf16_f32 v52, v52, v53
	v_cvt_pk_bf16_f32 v53, v54, v55
	v_cvt_pk_bf16_f32 v54, v60, v61
	v_cvt_pk_bf16_f32 v55, v58, v59
	global_store_dwordx4 v[56:57], v[52:55], off offset:256 nt

.LBB0_566:
	v_add_u32_e32 v36, 0xa0, v130
	v_ashrrev_i32_e32 v37, 31, v36
	v_lshlrev_b64 v[32:33], 6, v[36:37]
	v_lshl_add_u64 v[32:33], v[206:207], 0, v[32:33]
	s_mov_b64 s[40:41], -1
	s_waitcnt vmcnt(7)
	v_add_f32_e32 v32, v170, v171
	v_add_f32_e32 v33, v172, v173
	v_add_f32_e32 v32, v32, v33
	v_mov_b32_e32 v33, v32
	s_nop 1
	v_permlane16_swap_b32_e32 v32, v33
	v_add_f32_e32 v32, v32, v33
	v_mov_b32_e32 v33, v32
	s_nop 1
	v_permlane32_swap_b32_e32 v32, v33
	v_add_f32_e32 v32, v32, v33
	v_fmamk_f32 v32, v32, 0x3a800000, v225
	v_cmp_gt_f32_e32 vcc, s3, v32
	v_mul_f32_e32 v33, 0x4b800000, v32
	s_nop 0
	v_cndmask_b32_e32 v32, v32, v33, vcc
	v_rsq_f32_e32 v32, v32
	s_nop 0
	v_mul_f32_e32 v33, 0x45800000, v32
	v_cndmask_b32_e32 v34, v32, v33, vcc
	s_and_b64 vcc, exec, s[38:39]
	v_lshlrev_b64 v[32:33], 11, v[36:37]
	s_cbranch_vccnz .LBB0_568
	v_lshl_add_u64 v[36:37], s[26:27], 0, v[32:33]
	v_lshl_add_u64 v[36:37], s[68:69], 1, v[36:37]
	s_lshl_b32 s40, s62, 1
	s_mov_b32 s41, s69
	v_lshl_add_u64 v[36:37], v[36:37], 0, s[40:41]
	v_lshl_add_u64 v[40:41], v[36:37], 0, v[96:97]
	v_pk_mul_f32 v[38:39], v[30:31], v[34:35] op_sel_hi:[1,0]
	v_pk_mul_f32 v[36:37], v[28:29], v[34:35] op_sel_hi:[1,0]
	v_pk_mul_f32 v[42:43], v[22:23], v[34:35] op_sel_hi:[1,0]
	v_pk_mul_f32 v[44:45], v[20:21], v[34:35] op_sel_hi:[1,0]
	v_cvt_pk_bf16_f32 v36, v36, v37
	v_cvt_pk_bf16_f32 v37, v38, v39
	v_cvt_pk_bf16_f32 v38, v44, v45
	v_cvt_pk_bf16_f32 v39, v42, v43
	global_store_dwordx4 v[40:41], v[36:39], off nt
	v_pk_mul_f32 v[42:43], v[18:19], v[34:35] op_sel_hi:[1,0]
	v_pk_mul_f32 v[44:45], v[16:17], v[34:35] op_sel_hi:[1,0]
	v_pk_mul_f32 v[38:39], v[26:27], v[34:35] op_sel_hi:[1,0]
	v_pk_mul_f32 v[36:37], v[24:25], v[34:35] op_sel_hi:[1,0]
	s_mov_b64 s[40:41], 0
	v_cvt_pk_bf16_f32 v36, v36, v37
	v_cvt_pk_bf16_f32 v37, v38, v39
	v_cvt_pk_bf16_f32 v38, v44, v45
	v_cvt_pk_bf16_f32 v39, v42, v43
	global_store_dwordx4 v[40:41], v[36:39], off offset:256 nt

.LBB0_570:
	v_add_u32_e32 v20, 0xb0, v130
	v_ashrrev_i32_e32 v21, 31, v20
	v_lshlrev_b64 v[16:17], 6, v[20:21]
	v_lshl_add_u64 v[16:17], v[206:207], 0, v[16:17]
	s_mov_b64 s[40:41], -1
	s_waitcnt vmcnt(7)
	v_add_f32_e32 v16, v174, v175
	v_add_f32_e32 v17, v176, v177
	v_add_f32_e32 v16, v16, v17
	v_mov_b32_e32 v17, v16
	s_nop 1
	v_permlane16_swap_b32_e32 v16, v17
	v_add_f32_e32 v16, v16, v17
	v_mov_b32_e32 v17, v16
	s_nop 1
	v_permlane32_swap_b32_e32 v16, v17
	v_add_f32_e32 v16, v16, v17
	v_fmamk_f32 v16, v16, 0x3a800000, v225
	v_cmp_gt_f32_e32 vcc, s3, v16
	v_mul_f32_e32 v17, 0x4b800000, v16
	s_nop 0
	v_cndmask_b32_e32 v16, v16, v17, vcc
	v_rsq_f32_e32 v16, v16
	s_nop 0
	v_mul_f32_e32 v17, 0x45800000, v16
	v_cndmask_b32_e32 v18, v16, v17, vcc
	s_and_b64 vcc, exec, s[38:39]
	v_lshlrev_b64 v[16:17], 11, v[20:21]
	s_cbranch_vccz .LBB0_573
	s_andn2_b64 vcc, exec, s[40:41]
	s_cbranch_vccz .LBB0_574
